# v24 plus satisfied no-op waits removed in the attention loop copies and behind the GEMM phase barriers
# baseline (speedup 1.0000x reference)
; #define PG8_STAGE(bufoff, gbase, voff) do { _Pragma("unroll") for (int _i = 0; _i < 2; ++_i) \
;         __builtin_amdgcn_global_load_lds((const unsigned*)((const char*)(gbase) + (voff)[_i]), (LAS unsigned*)(lds + (bufoff) + ldsw + _i * 8192), 16, 0, 0); } while (0)
; #define PG8_LDA(dst, b, h) do { _Pragma("unroll") for (int m = 0; m < 4; ++m) _Pragma("unroll") for (int k = 0; k < 2; ++k) dst[m][k] = *(const LAS bf16x8*)(lds + PG8_SA(b, h) + aoff + m * 2048 + k * 1024); } while (0)
; #define PG8_LDB(dst, b, h) do { _Pragma("unroll") for (int n = 0; n < 2; ++n) _Pragma("unroll") for (int k = 0; k < 2; ++k) dst[n][k] = *(const LAS bf16x8*)(lds + PG8_SB(b, h) + boff + n * 2048 + k * 1024); } while (0)
; #define PG8_MMA(ai, bj, At, Bt) do { __builtin_amdgcn_s_setprio(1); _Pragma("unroll") for (int m = 0; m < 4; ++m) _Pragma("unroll") for (int n = 0; n < 2; ++n) _Pragma("unroll") for (int k = 0; k < 2; ++k) \
;         acc[ai][bj][m][n] = __builtin_amdgcn_mfma_f32_16x16x32_bf16(Bt[n][k], At[m][k], acc[ai][bj][m][n], 0, 0, 0); __builtin_amdgcn_s_setprio(0); } while (0)
; #define PG8_WAIT_V(n) asm volatile("s_waitcnt vmcnt(" #n ")" ::: "memory")
; #define PG8_WAIT_L(n) asm volatile("s_waitcnt lgkmcnt(" #n ")" ::: "memory")
; #define PG8_BAR __builtin_amdgcn_s_barrier()
; #define PG8_SCHED __builtin_amdgcn_sched_barrier(0)
; template <class Epi, class Sched>
; __device__ __forceinline__ void gemm_phase(LAS unsigned char* lds, const Gemm g, const Sched& S, const Epi& E, const int wid) {
;     ...
;             const bool last = (t == nt - 2);
;             const char* a1 = cA + (size_t)(t + 1) * kstep;
;             const char* a2 = last ? nA : cA + (size_t)(t + 2) * kstep; const char* b2 = last ? nB : cB + (size_t)(t + 2) * kstep;
;             const char* a3 = a2 + kstep; const char* b3 = b2 + kstep;
;             PG8_LDB(B0, 0, 0); PG8_LDB(B1, 0, 1); PG8_SCHED; PG8_LDA(At, 0, 0); PG8_STAGE(PG8_SA(1, 1), a1 + hstepA, voffA);
;             PG8_WAIT_V(8); PG8_WAIT_L(0); PG8_BAR; PG8_MMA(0, 0, At, B0); PG8_MMA(0, 1, At, B1); PG8_BAR; PG8_SCHED;
;             PG8_LDA(At, 0, 1); PG8_STAGE(PG8_SB(0, 0), b2, voffB); PG8_STAGE(PG8_SB(0, 1), b2 + hstepB, voffB); PG8_STAGE(PG8_SA(0, 0), a2, voffA);
;             PG8_WAIT_V(8); PG8_WAIT_L(0); PG8_BAR; PG8_MMA(1, 0, At, B0); PG8_MMA(1, 1, At, B1); PG8_BAR; PG8_SCHED;
.LBB0_247:
	v_add_u32_e32 v144, s76, v171
	ds_read_b128 v[128:131], v144
	ds_read_b128 v[132:135], v144 offset:1024
	ds_read_b128 v[192:195], v144 offset:2048
	ds_read_b128 v[196:199], v144 offset:3072
	v_add_u32_e32 v144, s77, v171
	ds_read_b128 v[200:203], v144
	ds_read_b128 v[204:207], v144 offset:1024
	ds_read_b128 v[208:211], v144 offset:2048
	ds_read_b128 v[212:215], v144 offset:3072
	s_add_u32 s58, s56, 0xfffc0080
	s_addc_u32 s59, s57, -1
	s_cmp_eq_u32 s86, 12
	s_cselect_b32 s61, s16, s59
	s_cselect_b32 s60, s47, s58
	s_cselect_b32 s59, s45, s85
	s_cselect_b32 s58, s53, s84
	v_lshl_add_u64 v[168:169], s[56:57], 0, v[160:161]
	s_add_i32 m0, s55, 0xc000
	ds_read_b128 v[216:219], v188
	ds_read_b128 v[220:223], v188 offset:1024
	ds_read_b128 v[224:227], v188 offset:2048
	ds_read_b128 v[228:231], v188 offset:3072
	ds_read_b128 v[232:235], v188 offset:4096
	ds_read_b128 v[236:239], v188 offset:5120
	ds_read_b128 v[240:243], v188 offset:6144
	ds_read_b128 v[244:247], v188 offset:7168
	global_load_lds_dwordx4 v[168:169], off
	v_lshl_add_u64 v[168:169], s[56:57], 0, v[162:163]
	s_add_i32 m0, s55, 0xe000
	s_nop 0
	global_load_lds_dwordx4 v[168:169], off
	s_waitcnt vmcnt(8)
	s_waitcnt lgkmcnt(0)
	s_barrier
	s_setprio 1
	v_mfma_f32_16x16x32_bf16 v[124:127], v[128:131], v[216:219], v[124:127]
	v_mfma_f32_16x16x32_bf16 v[120:123], v[192:195], v[216:219], v[120:123]
	v_mfma_f32_16x16x32_bf16 v[108:111], v[128:131], v[224:227], v[108:111]
	v_mfma_f32_16x16x32_bf16 v[104:107], v[192:195], v[224:227], v[104:107]
	v_mfma_f32_16x16x32_bf16 v[92:95], v[128:131], v[232:235], v[92:95]
	v_mfma_f32_16x16x32_bf16 v[88:91], v[192:195], v[232:235], v[88:91]
	v_mfma_f32_16x16x32_bf16 v[76:79], v[128:131], v[240:243], v[76:79]
	v_mfma_f32_16x16x32_bf16 v[72:75], v[192:195], v[240:243], v[72:75]
	v_mfma_f32_16x16x32_bf16 v[124:127], v[132:135], v[220:223], v[124:127]
	v_mfma_f32_16x16x32_bf16 v[120:123], v[196:199], v[220:223], v[120:123]
	v_mfma_f32_16x16x32_bf16 v[108:111], v[132:135], v[228:231], v[108:111]
	v_mfma_f32_16x16x32_bf16 v[104:107], v[196:199], v[228:231], v[104:107]
	v_mfma_f32_16x16x32_bf16 v[92:95], v[132:135], v[236:239], v[92:95]
	v_mfma_f32_16x16x32_bf16 v[88:91], v[196:199], v[236:239], v[88:91]
	v_mfma_f32_16x16x32_bf16 v[76:79], v[132:135], v[244:247], v[76:79]
	v_mfma_f32_16x16x32_bf16 v[72:75], v[196:199], v[244:247], v[72:75]
	v_mfma_f32_16x16x32_bf16 v[116:119], v[200:203], v[216:219], v[116:119]
	v_mfma_f32_16x16x32_bf16 v[112:115], v[208:211], v[216:219], v[112:115]
	v_mfma_f32_16x16x32_bf16 v[100:103], v[200:203], v[224:227], v[100:103]
	v_mfma_f32_16x16x32_bf16 v[96:99], v[208:211], v[224:227], v[96:99]
	v_mfma_f32_16x16x32_bf16 v[84:87], v[200:203], v[232:235], v[84:87]
	v_mfma_f32_16x16x32_bf16 v[80:83], v[208:211], v[232:235], v[80:83]
	v_mfma_f32_16x16x32_bf16 v[68:71], v[200:203], v[240:243], v[68:71]
	v_mfma_f32_16x16x32_bf16 v[64:67], v[208:211], v[240:243], v[64:67]
	v_mfma_f32_16x16x32_bf16 v[116:119], v[204:207], v[220:223], v[116:119]
	v_mfma_f32_16x16x32_bf16 v[112:115], v[212:215], v[220:223], v[112:115]
	v_mfma_f32_16x16x32_bf16 v[100:103], v[204:207], v[228:231], v[100:103]
	v_mfma_f32_16x16x32_bf16 v[96:99], v[212:215], v[228:231], v[96:99]
	v_mfma_f32_16x16x32_bf16 v[84:87], v[204:207], v[236:239], v[84:87]
	v_mfma_f32_16x16x32_bf16 v[80:83], v[212:215], v[236:239], v[80:83]
	v_mfma_f32_16x16x32_bf16 v[68:71], v[204:207], v[244:247], v[68:71]
	v_mfma_f32_16x16x32_bf16 v[64:67], v[212:215], v[244:247], v[64:67]
	s_setprio 0
	s_barrier
	s_add_i32 s87, s76, s65
	v_lshl_add_u64 v[168:169], s[58:59], 0, v[138:139]
	s_mov_b32 m0, s87
	ds_read_b128 v[216:219], v188 offset:16384
	ds_read_b128 v[220:223], v188 offset:17408
	ds_read_b128 v[224:227], v188 offset:18432
	ds_read_b128 v[228:231], v188 offset:19456
	ds_read_b128 v[232:235], v188 offset:20480
	ds_read_b128 v[236:239], v188 offset:21504
	ds_read_b128 v[240:243], v188 offset:22528
	ds_read_b128 v[244:247], v188 offset:23552
	global_load_lds_dwordx4 v[168:169], off
	s_add_i32 m0, s87, 0x2000
	s_add_u32 s88, s58, 0x40000
	v_lshl_add_u64 v[248:249], s[58:59], 0, v[142:143]
	s_addc_u32 s89, s59, 0
	s_add_i32 s87, s77, s65
	global_load_lds_dwordx4 v[248:249], off
	v_lshl_add_u64 v[250:251], s[88:89], 0, v[138:139]
	s_mov_b32 m0, s87
	v_lshl_add_u64 v[252:253], s[60:61], 0, v[140:141]
	global_load_lds_dwordx4 v[250:251], off
	v_lshl_add_u64 v[250:251], s[88:89], 0, v[142:143]
	s_add_i32 m0, s87, 0x2000
	s_nop 0
	global_load_lds_dwordx4 v[250:251], off
	v_lshl_add_u64 v[250:251], s[60:61], 0, v[136:137]
	s_mov_b32 m0, s55
	s_nop 0
	global_load_lds_dwordx4 v[250:251], off
	s_mov_b32 m0, s66
	s_nop 0
	global_load_lds_dwordx4 v[252:253], off
	s_waitcnt vmcnt(8)
	s_waitcnt lgkmcnt(0)
	s_barrier
; #define PG8_STAGE(bufoff, gbase, voff) do { _Pragma("unroll") for (int _i = 0; _i < 2; ++_i) \
;         __builtin_amdgcn_global_load_lds((const unsigned*)((const char*)(gbase) + (voff)[_i]), (LAS unsigned*)(lds + (bufoff) + ldsw + _i * 8192), 16, 0, 0); } while (0)
; #define PG8_LDA(dst, b, h) do { _Pragma("unroll") for (int m = 0; m < 4; ++m) _Pragma("unroll") for (int k = 0; k < 2; ++k) dst[m][k] = *(const LAS bf16x8*)(lds + PG8_SA(b, h) + aoff + m * 2048 + k * 1024); } while (0)
; #define PG8_LDB(dst, b, h) do { _Pragma("unroll") for (int n = 0; n < 2; ++n) _Pragma("unroll") for (int k = 0; k < 2; ++k) dst[n][k] = *(const LAS bf16x8*)(lds + PG8_SB(b, h) + boff + n * 2048 + k * 1024); } while (0)
; #define PG8_MMA(ai, bj, At, Bt) do { __builtin_amdgcn_s_setprio(1); _Pragma("unroll") for (int m = 0; m < 4; ++m) _Pragma("unroll") for (int n = 0; n < 2; ++n) _Pragma("unroll") for (int k = 0; k < 2; ++k) \
;         acc[ai][bj][m][n] = __builtin_amdgcn_mfma_f32_16x16x32_bf16(Bt[n][k], At[m][k], acc[ai][bj][m][n], 0, 0, 0); __builtin_amdgcn_s_setprio(0); } while (0)
; #define PG8_WAIT_V(n) asm volatile("s_waitcnt vmcnt(" #n ")" ::: "memory")
; #define PG8_WAIT_L(n) asm volatile("s_waitcnt lgkmcnt(" #n ")" ::: "memory")
; #define PG8_BAR __builtin_amdgcn_s_barrier()
; #define PG8_SCHED __builtin_amdgcn_sched_barrier(0)
; template <class Epi, class Sched>
; __device__ __forceinline__ void gemm_phase(LAS unsigned char* lds, const Gemm g, const Sched& S, const Epi& E, const int wid) {
;     ...
;             PG8_WAIT_V(8); PG8_WAIT_L(0); PG8_BAR; PG8_MMA(1, 0, At, B0); PG8_MMA(1, 1, At, B1); PG8_BAR; PG8_SCHED;
;             PG8_LDB(B0, 1, 0); PG8_LDB(B1, 1, 1); PG8_SCHED; PG8_LDA(At, 1, 0); PG8_STAGE(PG8_SA(0, 1), a2 + hstepA, voffA);
;             PG8_WAIT_V(8); PG8_WAIT_L(0); PG8_BAR; PG8_MMA(0, 0, At, B0); PG8_MMA(0, 1, At, B1); PG8_BAR; PG8_SCHED;
	s_setprio 1
	v_mfma_f32_16x16x32_bf16 v[60:63], v[128:131], v[216:219], v[60:63]
	v_mfma_f32_16x16x32_bf16 v[56:59], v[192:195], v[216:219], v[56:59]
	v_mfma_f32_16x16x32_bf16 v[44:47], v[128:131], v[224:227], v[44:47]
	v_mfma_f32_16x16x32_bf16 v[40:43], v[192:195], v[224:227], v[40:43]
	v_mfma_f32_16x16x32_bf16 v[28:31], v[128:131], v[232:235], v[28:31]
	v_mfma_f32_16x16x32_bf16 v[24:27], v[192:195], v[232:235], v[24:27]
	v_mfma_f32_16x16x32_bf16 v[12:15], v[128:131], v[240:243], v[12:15]
	v_mfma_f32_16x16x32_bf16 v[8:11], v[192:195], v[240:243], v[8:11]
	v_mfma_f32_16x16x32_bf16 v[60:63], v[132:135], v[220:223], v[60:63]
	v_mfma_f32_16x16x32_bf16 v[56:59], v[196:199], v[220:223], v[56:59]
	v_mfma_f32_16x16x32_bf16 v[44:47], v[132:135], v[228:231], v[44:47]
	v_mfma_f32_16x16x32_bf16 v[40:43], v[196:199], v[228:231], v[40:43]
	v_mfma_f32_16x16x32_bf16 v[28:31], v[132:135], v[236:239], v[28:31]
	v_mfma_f32_16x16x32_bf16 v[24:27], v[196:199], v[236:239], v[24:27]
	v_mfma_f32_16x16x32_bf16 v[12:15], v[132:135], v[244:247], v[12:15]
	v_mfma_f32_16x16x32_bf16 v[8:11], v[196:199], v[244:247], v[8:11]
	v_mfma_f32_16x16x32_bf16 v[52:55], v[200:203], v[216:219], v[52:55]
	v_mfma_f32_16x16x32_bf16 v[48:51], v[208:211], v[216:219], v[48:51]
	v_mfma_f32_16x16x32_bf16 v[36:39], v[200:203], v[224:227], v[36:39]
	v_mfma_f32_16x16x32_bf16 v[32:35], v[208:211], v[224:227], v[32:35]
	v_mfma_f32_16x16x32_bf16 v[20:23], v[200:203], v[232:235], v[20:23]
	v_mfma_f32_16x16x32_bf16 v[16:19], v[208:211], v[232:235], v[16:19]
	v_mfma_f32_16x16x32_bf16 v[4:7], v[200:203], v[240:243], v[4:7]
	v_mfma_f32_16x16x32_bf16 v[0:3], v[208:211], v[240:243], v[0:3]
	v_mfma_f32_16x16x32_bf16 v[52:55], v[204:207], v[220:223], v[52:55]
	v_mfma_f32_16x16x32_bf16 v[48:51], v[212:215], v[220:223], v[48:51]
	v_mfma_f32_16x16x32_bf16 v[36:39], v[204:207], v[228:231], v[36:39]
	v_mfma_f32_16x16x32_bf16 v[32:35], v[212:215], v[228:231], v[32:35]
	v_mfma_f32_16x16x32_bf16 v[20:23], v[204:207], v[236:239], v[20:23]
	v_mfma_f32_16x16x32_bf16 v[16:19], v[212:215], v[236:239], v[16:19]
	v_mfma_f32_16x16x32_bf16 v[4:7], v[204:207], v[244:247], v[4:7]
	v_mfma_f32_16x16x32_bf16 v[0:3], v[212:215], v[244:247], v[0:3]
	s_setprio 0
	s_barrier
	s_add_i32 s87, 0, 0x18000
	v_add_u32_e32 v144, s87, v171
	s_add_i32 s88, 0, 0x1c000
	ds_read_b128 v[128:131], v144
	ds_read_b128 v[132:135], v144 offset:1024
	ds_read_b128 v[192:195], v144 offset:2048
	ds_read_b128 v[196:199], v144 offset:3072
	v_add_u32_e32 v144, s88, v171
	ds_read_b128 v[200:203], v144
	ds_read_b128 v[204:207], v144 offset:1024
	ds_read_b128 v[208:211], v144 offset:2048
	ds_read_b128 v[212:215], v144 offset:3072
	s_add_u32 s60, s60, 0x40000
	s_addc_u32 s61, s61, 0
	s_mov_b32 m0, s67
	v_lshl_add_u64 v[254:255], s[60:61], 0, v[136:137]
	ds_read_b128 v[216:219], v188 offset:32768
	ds_read_b128 v[220:223], v188 offset:33792
	ds_read_b128 v[224:227], v188 offset:34816
	ds_read_b128 v[228:231], v188 offset:35840
	ds_read_b128 v[232:235], v188 offset:36864
	ds_read_b128 v[236:239], v188 offset:37888
	ds_read_b128 v[240:243], v188 offset:38912
	ds_read_b128 v[244:247], v188 offset:39936
	global_load_lds_dwordx4 v[254:255], off
	v_lshl_add_u64 v[254:255], s[60:61], 0, v[140:141]
	s_mov_b32 m0, s68
	s_nop 0
	global_load_lds_dwordx4 v[254:255], off
	s_waitcnt vmcnt(8)
	s_waitcnt lgkmcnt(0)
	s_barrier
	s_setprio 1
	v_mfma_f32_16x16x32_bf16 v[124:127], v[128:131], v[216:219], v[124:127]
	v_mfma_f32_16x16x32_bf16 v[120:123], v[192:195], v[216:219], v[120:123]
	v_mfma_f32_16x16x32_bf16 v[108:111], v[128:131], v[224:227], v[108:111]
	v_mfma_f32_16x16x32_bf16 v[104:107], v[192:195], v[224:227], v[104:107]
	v_mfma_f32_16x16x32_bf16 v[92:95], v[128:131], v[232:235], v[92:95]
	v_mfma_f32_16x16x32_bf16 v[88:91], v[192:195], v[232:235], v[88:91]
	v_mfma_f32_16x16x32_bf16 v[76:79], v[128:131], v[240:243], v[76:79]
	v_mfma_f32_16x16x32_bf16 v[72:75], v[192:195], v[240:243], v[72:75]
	v_mfma_f32_16x16x32_bf16 v[124:127], v[132:135], v[220:223], v[124:127]
	v_mfma_f32_16x16x32_bf16 v[120:123], v[196:199], v[220:223], v[120:123]
	v_mfma_f32_16x16x32_bf16 v[108:111], v[132:135], v[228:231], v[108:111]
	v_mfma_f32_16x16x32_bf16 v[104:107], v[196:199], v[228:231], v[104:107]
	v_mfma_f32_16x16x32_bf16 v[92:95], v[132:135], v[236:239], v[92:95]
	v_mfma_f32_16x16x32_bf16 v[88:91], v[196:199], v[236:239], v[88:91]
	v_mfma_f32_16x16x32_bf16 v[76:79], v[132:135], v[244:247], v[76:79]
	v_mfma_f32_16x16x32_bf16 v[72:75], v[196:199], v[244:247], v[72:75]
	v_mfma_f32_16x16x32_bf16 v[116:119], v[200:203], v[216:219], v[116:119]
	v_mfma_f32_16x16x32_bf16 v[112:115], v[208:211], v[216:219], v[112:115]
	v_mfma_f32_16x16x32_bf16 v[100:103], v[200:203], v[224:227], v[100:103]
	v_mfma_f32_16x16x32_bf16 v[96:99], v[208:211], v[224:227], v[96:99]
	v_mfma_f32_16x16x32_bf16 v[84:87], v[200:203], v[232:235], v[84:87]
	v_mfma_f32_16x16x32_bf16 v[80:83], v[208:211], v[232:235], v[80:83]
	v_mfma_f32_16x16x32_bf16 v[68:71], v[200:203], v[240:243], v[68:71]
	v_mfma_f32_16x16x32_bf16 v[64:67], v[208:211], v[240:243], v[64:67]
	v_mfma_f32_16x16x32_bf16 v[116:119], v[204:207], v[220:223], v[116:119]
	v_mfma_f32_16x16x32_bf16 v[112:115], v[212:215], v[220:223], v[112:115]
	v_mfma_f32_16x16x32_bf16 v[100:103], v[204:207], v[228:231], v[100:103]
	v_mfma_f32_16x16x32_bf16 v[96:99], v[212:215], v[228:231], v[96:99]
	v_mfma_f32_16x16x32_bf16 v[84:87], v[204:207], v[236:239], v[84:87]
	v_mfma_f32_16x16x32_bf16 v[80:83], v[212:215], v[236:239], v[80:83]
	v_mfma_f32_16x16x32_bf16 v[68:71], v[204:207], v[244:247], v[68:71]
	v_mfma_f32_16x16x32_bf16 v[64:67], v[212:215], v[244:247], v[64:67]
	s_setprio 0
	s_barrier
; #define PG8_STAGE(bufoff, gbase, voff) do { _Pragma("unroll") for (int _i = 0; _i < 2; ++_i) \
;         __builtin_amdgcn_global_load_lds((const unsigned*)((const char*)(gbase) + (voff)[_i]), (LAS unsigned*)(lds + (bufoff) + ldsw + _i * 8192), 16, 0, 0); } while (0)
; #define PG8_LDA(dst, b, h) do { _Pragma("unroll") for (int m = 0; m < 4; ++m) _Pragma("unroll") for (int k = 0; k < 2; ++k) dst[m][k] = *(const LAS bf16x8*)(lds + PG8_SA(b, h) + aoff + m * 2048 + k * 1024); } while (0)
; #define PG8_MMA(ai, bj, At, Bt) do { __builtin_amdgcn_s_setprio(1); _Pragma("unroll") for (int m = 0; m < 4; ++m) _Pragma("unroll") for (int n = 0; n < 2; ++n) _Pragma("unroll") for (int k = 0; k < 2; ++k) \
;         acc[ai][bj][m][n] = __builtin_amdgcn_mfma_f32_16x16x32_bf16(Bt[n][k], At[m][k], acc[ai][bj][m][n], 0, 0, 0); __builtin_amdgcn_s_setprio(0); } while (0)
; #define PG8_WAIT_V(n) asm volatile("s_waitcnt vmcnt(" #n ")" ::: "memory")
; #define PG8_WAIT_L(n) asm volatile("s_waitcnt lgkmcnt(" #n ")" ::: "memory")
; #define PG8_BAR __builtin_amdgcn_s_barrier()
; #define PG8_SCHED __builtin_amdgcn_sched_barrier(0)
; template <class Epi, class Sched>
; __device__ __forceinline__ void gemm_phase(LAS unsigned char* lds, const Gemm g, const Sched& S, const Epi& E, const int wid) {
;     ...
;             PG8_LDA(At, 1, 1); PG8_STAGE(PG8_SB(1, 0), b3, voffB); PG8_STAGE(PG8_SB(1, 1), b3 + hstepB, voffB); PG8_STAGE(PG8_SA(1, 0), a3, voffA);
;             PG8_WAIT_V(8); PG8_WAIT_L(0); PG8_BAR; PG8_MMA(1, 0, At, B0); PG8_MMA(1, 1, At, B1); PG8_BAR; PG8_SCHED;
;         }
;         if (wr == 0) PG8_BAR;
	s_add_i32 s60, s87, s65
	v_lshl_add_u64 v[168:169], v[168:169], 0, s[22:23]
	s_mov_b32 m0, s60
	ds_read_b128 v[216:219], v188 offset:49152
	ds_read_b128 v[220:223], v188 offset:50176
	ds_read_b128 v[224:227], v188 offset:51200
	ds_read_b128 v[228:231], v188 offset:52224
	ds_read_b128 v[232:235], v188 offset:53248
	ds_read_b128 v[236:239], v188 offset:54272
	ds_read_b128 v[240:243], v188 offset:55296
	ds_read_b128 v[244:247], v188 offset:56320
	global_load_lds_dwordx4 v[168:169], off
	s_add_i32 m0, s60, 0x2000
	s_add_u32 s58, s58, 0x40080
	v_lshl_add_u64 v[168:169], v[248:249], 0, s[22:23]
	s_addc_u32 s59, s59, 0
	s_add_i32 s60, s88, s65
	global_load_lds_dwordx4 v[168:169], off
	v_lshl_add_u64 v[168:169], s[58:59], 0, v[138:139]
	s_mov_b32 m0, s60
	s_nop 0
	global_load_lds_dwordx4 v[168:169], off
	v_lshl_add_u64 v[168:169], s[58:59], 0, v[142:143]
	s_add_i32 m0, s60, 0x2000
	s_nop 0
	global_load_lds_dwordx4 v[168:169], off
	v_lshl_add_u64 v[168:169], v[250:251], 0, s[22:23]
	s_mov_b32 m0, s70
	s_nop 0
	global_load_lds_dwordx4 v[168:169], off
	v_lshl_add_u64 v[168:169], v[252:253], 0, s[22:23]
	s_mov_b32 m0, s71
	s_nop 0
	global_load_lds_dwordx4 v[168:169], off
	s_waitcnt vmcnt(8)
	s_waitcnt lgkmcnt(0)
	s_barrier
	s_setprio 1
	v_mfma_f32_16x16x32_bf16 v[60:63], v[128:131], v[216:219], v[60:63]
	v_mfma_f32_16x16x32_bf16 v[56:59], v[192:195], v[216:219], v[56:59]
	v_mfma_f32_16x16x32_bf16 v[44:47], v[128:131], v[224:227], v[44:47]
	v_mfma_f32_16x16x32_bf16 v[40:43], v[192:195], v[224:227], v[40:43]
	v_mfma_f32_16x16x32_bf16 v[28:31], v[128:131], v[232:235], v[28:31]
	v_mfma_f32_16x16x32_bf16 v[24:27], v[192:195], v[232:235], v[24:27]
	v_mfma_f32_16x16x32_bf16 v[12:15], v[128:131], v[240:243], v[12:15]
	v_mfma_f32_16x16x32_bf16 v[8:11], v[192:195], v[240:243], v[8:11]
	v_mfma_f32_16x16x32_bf16 v[60:63], v[132:135], v[220:223], v[60:63]
	v_mfma_f32_16x16x32_bf16 v[56:59], v[196:199], v[220:223], v[56:59]
	v_mfma_f32_16x16x32_bf16 v[44:47], v[132:135], v[228:231], v[44:47]
	v_mfma_f32_16x16x32_bf16 v[40:43], v[196:199], v[228:231], v[40:43]
	v_mfma_f32_16x16x32_bf16 v[28:31], v[132:135], v[236:239], v[28:31]
	v_mfma_f32_16x16x32_bf16 v[24:27], v[196:199], v[236:239], v[24:27]
	v_mfma_f32_16x16x32_bf16 v[12:15], v[132:135], v[244:247], v[12:15]
	v_mfma_f32_16x16x32_bf16 v[8:11], v[196:199], v[244:247], v[8:11]
	v_mfma_f32_16x16x32_bf16 v[52:55], v[200:203], v[216:219], v[52:55]
	v_mfma_f32_16x16x32_bf16 v[48:51], v[208:211], v[216:219], v[48:51]
	v_mfma_f32_16x16x32_bf16 v[36:39], v[200:203], v[224:227], v[36:39]
	v_mfma_f32_16x16x32_bf16 v[32:35], v[208:211], v[224:227], v[32:35]
	v_mfma_f32_16x16x32_bf16 v[20:23], v[200:203], v[232:235], v[20:23]
	v_mfma_f32_16x16x32_bf16 v[16:19], v[208:211], v[232:235], v[16:19]
	v_mfma_f32_16x16x32_bf16 v[4:7], v[200:203], v[240:243], v[4:7]
	v_mfma_f32_16x16x32_bf16 v[0:3], v[208:211], v[240:243], v[0:3]
	v_mfma_f32_16x16x32_bf16 v[52:55], v[204:207], v[220:223], v[52:55]
	v_mfma_f32_16x16x32_bf16 v[48:51], v[212:215], v[220:223], v[48:51]
	v_mfma_f32_16x16x32_bf16 v[36:39], v[204:207], v[228:231], v[36:39]
	v_mfma_f32_16x16x32_bf16 v[32:35], v[212:215], v[228:231], v[32:35]
	v_mfma_f32_16x16x32_bf16 v[20:23], v[204:207], v[236:239], v[20:23]
	v_mfma_f32_16x16x32_bf16 v[16:19], v[212:215], v[236:239], v[16:19]
	v_mfma_f32_16x16x32_bf16 v[4:7], v[204:207], v[244:247], v[4:7]
	v_mfma_f32_16x16x32_bf16 v[0:3], v[212:215], v[244:247], v[0:3]
	s_setprio 0
	s_barrier
	s_add_i32 s86, s86, 2
	s_add_u32 s56, s56, 0x100
	s_addc_u32 s57, s57, 0
	s_add_u32 s84, s84, 0x100
	s_addc_u32 s85, s85, 0
	s_cmp_gt_u32 s86, 13
	s_cbranch_scc0 .LBB0_247
	s_and_b64 vcc, exec, s[34:35]
	s_cbranch_vccnz .LBB0_252
	s_cmp_gt_i32 s54, 4
	s_mov_b64 s[56:57], -1
	s_cbranch_scc1 .LBB0_253

; __device__ __forceinline__ float max32(const f32x16& p0, const f32x16& p1) {
;   float m = p0[0]; for (int r = 1; r < 16; ++r) m = fmaxf(m, p0[r]); for (int r = 0; r < 16; ++r) m = fmaxf(m, p1[r]);
;   { auto rr = __builtin_amdgcn_permlane32_swap(__float_as_uint(m), __float_as_uint(m), false, false);
;     m = fmaxf(__uint_as_float(rr[0]), __uint_as_float(rr[1])); }
;   return m;
; }
; __device__ __forceinline__ void adjustSM(f32x16& p0, f32x16& p1, f32x16& nm, float& alpha, const float pmax) {
;   alpha = 1.f;
;   if (__builtin_expect(__any(pmax > PSHIFT + THR2), 0)) {
;     const float delta = (pmax > PSHIFT + THR2) ? (pmax - PSHIFT) : 0.f;
;     alpha = __builtin_amdgcn_exp2f(-delta);
;     for (int r = 0; r < 16; ++r) { p0[r] -= delta; p1[r] -= delta; nm[r] -= delta; }
;   }
; }
; __device__ __forceinline__ void partialSM_first(f32x16& p0, f32x16& p1, f32x16& nm) {
;   const float delta = max32(p0, p1) - PSHIFT;
;   for (int r = 0; r < 16; ++r) { p0[r] -= delta; p1[r] -= delta; nm[r] -= delta; }
;   for (int r = 0; r < 16; ++r) p0[r] = __builtin_amdgcn_exp2f(p0[r]);
; }
; __device__ __forceinline__ void finishSM(f32x16& p0, f32x16& p1, v8i& pf) {
;   for (int r = 0; r < 16; ++r) p1[r] = __builtin_amdgcn_exp2f(p1[r]);
; #pragma unroll
;   for (int j = 0; j < 4; ++j) {
;     int a = __builtin_amdgcn_cvt_pk_fp8_f32(p0[4 * j], p0[4 * j + 1], 0, false); a = __builtin_amdgcn_cvt_pk_fp8_f32(p0[4 * j + 2], p0[4 * j + 3], a, true);
;     int b = __builtin_amdgcn_cvt_pk_fp8_f32(p1[4 * j], p1[4 * j + 1], 0, false); b = __builtin_amdgcn_cvt_pk_fp8_f32(p1[4 * j + 2], p1[4 * j + 3], b, true);
;     auto rr = __builtin_amdgcn_permlane32_swap((unsigned)a, (unsigned)b, false, false);
;     pf[2 * j] = (int)rr[0]; pf[2 * j + 1] = (int)rr[1]; }
; }
; __device__ __forceinline__ void qkt(f32x16& p0, f32x16& p1, const f32x16& nm, const char* Ks, const v8i* qr, int ko, int c00, int c01, int c10, int c11) {
;   { const v8i a0 = ld32(Ks + ko + c00, Ks + ko + c01), a1 = ld32(Ks + 4096 + ko + c00, Ks + 4096 + ko + c01);
;     p0 = MFMA8Q(a0, qr[0], nm); p1 = MFMA8Q(a1, qr[0], nm); }
;   { const v8i a0 = ld32(Ks + ko + c10, Ks + ko + c11), a1 = ld32(Ks + 4096 + ko + c10, Ks + 4096 + ko + c11);
;     p0 = MFMA8Q(a0, qr[1], p0); p1 = MFMA8Q(a1, qr[1], p1); }
; }
; __device__ __forceinline__ void pv_load(v8i* vf, const char* Vs, int vo, int e0, int e1) {
; #pragma unroll
.LBB0_374:
	ds_read_b128 v[2:5], v242 offset:40960
	ds_read_b128 v[6:9], v243 offset:40960
	ds_read_b128 v[128:131], v242 offset:45056
	ds_read_b128 v[132:135], v243 offset:45056
	ds_read_b128 v[194:197], v244 offset:40960
	ds_read_b128 v[198:201], v245 offset:40960
	ds_read_b128 v[246:249], v244 offset:45056
	ds_read_b128 v[250:253], v245 offset:45056
	v_exp_f32_e32 v1, v112
	v_exp_f32_e32 v10, v113
	v_exp_f32_e32 v11, v114
	v_exp_f32_e32 v12, v115
	s_waitcnt lgkmcnt(6)
	s_setprio 1
	v_mfma_scale_f32_32x32x64_f8f6f4 v[160:175], v[2:9], v[176:183], v[96:111], v240, v239 op_sel_hi:[0,0,0]
	v_exp_f32_e32 v6, v116
	v_exp_f32_e32 v7, v117
	v_exp_f32_e32 v8, v118
	v_exp_f32_e32 v9, v119
	v_cvt_pk_fp8_f32 v5, v6, v7
	v_cvt_pk_fp8_f32 v3, v1, v10
	v_cvt_pk_fp8_f32 v5, v8, v9 op_sel:[0,0,1]
	s_waitcnt lgkmcnt(4)
	v_mfma_scale_f32_32x32x64_f8f6f4 v[128:143], v[128:135], v[176:183], v[96:111], v240, v239 op_sel_hi:[0,0,0]
	v_exp_f32_e32 v13, v120
	v_exp_f32_e32 v14, v121
	v_exp_f32_e32 v15, v122
	v_exp_f32_e32 v112, v123
	v_cvt_pk_fp8_f32 v2, v144, v145
	v_cvt_pk_fp8_f32 v4, v148, v149
	v_cvt_pk_fp8_f32 v6, v152, v153
	v_cvt_pk_fp8_f32 v7, v13, v14
	v_cvt_pk_fp8_f32 v8, v156, v157
	v_cvt_pk_fp8_f32 v2, v146, v147 op_sel:[0,0,1]
	v_cvt_pk_fp8_f32 v3, v11, v12 op_sel:[0,0,1]
	v_cvt_pk_fp8_f32 v4, v150, v151 op_sel:[0,0,1]
	v_cvt_pk_fp8_f32 v6, v154, v155 op_sel:[0,0,1]
	v_cvt_pk_fp8_f32 v7, v15, v112 op_sel:[0,0,1]
	v_cvt_pk_fp8_f32 v8, v158, v159 op_sel:[0,0,1]
	s_waitcnt lgkmcnt(2)
	v_mfma_scale_f32_32x32x64_f8f6f4 v[160:175], v[194:201], v[184:191], v[160:175], v240, v239 op_sel_hi:[0,0,0]
	v_exp_f32_e32 v113, v124
	v_exp_f32_e32 v114, v125
	v_exp_f32_e32 v1, v126
	v_exp_f32_e32 v10, v127
	v_cvt_pk_fp8_f32 v9, v113, v114
	s_waitcnt lgkmcnt(0)
	v_cvt_pk_fp8_f32 v9, v1, v10 op_sel:[0,0,1]
	v_mfma_scale_f32_32x32x64_f8f6f4 v[128:143], v[246:253], v[184:191], v[128:143], v240, v239 op_sel_hi:[0,0,0]
	s_setprio 0
	s_add_i32 m0, s68, 0xe000
	s_nop 0
	global_load_lds_dwordx4 v192, s[98:99]
	s_add_i32 m0, s68, 0x6000
	s_nop 0
	global_load_lds_dwordx4 v193, s[100:101]
	ds_read_b128 v[194:197], v254
	ds_read_b128 v[148:151], v254 offset:2048
	ds_read_b128 v[198:201], v255
	ds_read_b128 v[152:155], v255 offset:2048
	ds_read_b128 v[120:123], v254 offset:4096
	ds_read_b128 v[112:115], v254 offset:6144
	ds_read_b128 v[124:127], v255 offset:4096
	ds_read_b128 v[116:119], v255 offset:6144
	v_max_f32_e32 v1, v160, v161
	v_max3_f32 v1, v1, v162, v163
	v_max3_f32 v1, v1, v164, v165
	v_max3_f32 v1, v1, v166, v167
	v_max3_f32 v1, v1, v168, v169
	v_max3_f32 v1, v1, v170, v171
	v_max3_f32 v1, v1, v172, v173
	v_max3_f32 v1, v1, v174, v175
	v_max3_f32 v1, v1, v128, v129
	v_max3_f32 v1, v1, v130, v131
	v_max3_f32 v1, v1, v132, v133
	v_max3_f32 v1, v1, v134, v135
	v_max3_f32 v1, v1, v136, v137
	v_max3_f32 v1, v1, v138, v139
	v_max3_f32 v1, v1, v140, v141
	v_max3_f32 v1, v1, v142, v143
	v_cmp_lt_f32_e32 vcc, s80, v1
	s_cbranch_vccnz .LBB0_383

; __device__ __forceinline__ float max32(const f32x16& p0, const f32x16& p1) {
;   float m = p0[0]; for (int r = 1; r < 16; ++r) m = fmaxf(m, p0[r]); for (int r = 0; r < 16; ++r) m = fmaxf(m, p1[r]);
;   { auto rr = __builtin_amdgcn_permlane32_swap(__float_as_uint(m), __float_as_uint(m), false, false);
;     m = fmaxf(__uint_as_float(rr[0]), __uint_as_float(rr[1])); }
;   return m;
; }
; __device__ __forceinline__ void adjustSM(f32x16& p0, f32x16& p1, f32x16& nm, float& alpha, const float pmax) {
;   alpha = 1.f;
;   if (__builtin_expect(__any(pmax > PSHIFT + THR2), 0)) {
;     const float delta = (pmax > PSHIFT + THR2) ? (pmax - PSHIFT) : 0.f;
;     alpha = __builtin_amdgcn_exp2f(-delta);
;     for (int r = 0; r < 16; ++r) { p0[r] -= delta; p1[r] -= delta; nm[r] -= delta; }
;   }
; }
; __device__ __forceinline__ void partialSM_first(f32x16& p0, f32x16& p1, f32x16& nm) {
;   const float delta = max32(p0, p1) - PSHIFT;
;   for (int r = 0; r < 16; ++r) { p0[r] -= delta; p1[r] -= delta; nm[r] -= delta; }
;   for (int r = 0; r < 16; ++r) p0[r] = __builtin_amdgcn_exp2f(p0[r]);
; }
; __device__ __forceinline__ void finishSM(f32x16& p0, f32x16& p1, v8i& pf) {
;   for (int r = 0; r < 16; ++r) p1[r] = __builtin_amdgcn_exp2f(p1[r]);
; #pragma unroll
;   for (int j = 0; j < 4; ++j) {
;     int a = __builtin_amdgcn_cvt_pk_fp8_f32(p0[4 * j], p0[4 * j + 1], 0, false); a = __builtin_amdgcn_cvt_pk_fp8_f32(p0[4 * j + 2], p0[4 * j + 3], a, true);
;     int b = __builtin_amdgcn_cvt_pk_fp8_f32(p1[4 * j], p1[4 * j + 1], 0, false); b = __builtin_amdgcn_cvt_pk_fp8_f32(p1[4 * j + 2], p1[4 * j + 3], b, true);
;     auto rr = __builtin_amdgcn_permlane32_swap((unsigned)a, (unsigned)b, false, false);
;     pf[2 * j] = (int)rr[0]; pf[2 * j + 1] = (int)rr[1]; }
; }
; __device__ __forceinline__ void qkt(f32x16& p0, f32x16& p1, const f32x16& nm, const char* Ks, const v8i* qr, int ko, int c00, int c01, int c10, int c11) {
;   { const v8i a0 = ld32(Ks + ko + c00, Ks + ko + c01), a1 = ld32(Ks + 4096 + ko + c00, Ks + 4096 + ko + c01);
;     p0 = MFMA8Q(a0, qr[0], nm); p1 = MFMA8Q(a1, qr[0], nm); }
;   { const v8i a0 = ld32(Ks + ko + c10, Ks + ko + c11), a1 = ld32(Ks + 4096 + ko + c10, Ks + 4096 + ko + c11);
;     p0 = MFMA8Q(a0, qr[1], p0); p1 = MFMA8Q(a1, qr[1], p1); }
; }
; __device__ __forceinline__ void pv_load(v8i* vf, const char* Vs, int vo, int e0, int e1) {
; #pragma unroll
.LBB0_379:
	s_waitcnt lgkmcnt(0)
	s_barrier
	ds_read_b128 v[2:5], v242 offset:49152
	ds_read_b128 v[6:9], v243 offset:49152
	ds_read_b128 v[112:115], v242 offset:53248
	ds_read_b128 v[116:119], v243 offset:53248
	ds_read_b128 v[194:197], v244 offset:49152
	ds_read_b128 v[198:201], v245 offset:49152
	ds_read_b128 v[246:249], v244 offset:53248
	ds_read_b128 v[250:253], v245 offset:53248
	v_exp_f32_e32 v1, v128
	v_exp_f32_e32 v10, v129
	v_exp_f32_e32 v11, v130
	v_exp_f32_e32 v12, v131
	s_waitcnt lgkmcnt(6)
	s_setprio 1
	v_mfma_scale_f32_32x32x64_f8f6f4 v[160:175], v[2:9], v[176:183], v[96:111], v240, v239 op_sel_hi:[0,0,0]
	v_exp_f32_e32 v6, v132
	v_exp_f32_e32 v7, v133
	v_exp_f32_e32 v8, v134
	v_exp_f32_e32 v9, v135
	v_cvt_pk_fp8_f32 v5, v6, v7
	v_cvt_pk_fp8_f32 v2, v144, v145
	v_cvt_pk_fp8_f32 v5, v8, v9 op_sel:[0,0,1]
	s_waitcnt lgkmcnt(4)
	v_mfma_scale_f32_32x32x64_f8f6f4 v[112:127], v[112:119], v[176:183], v[96:111], v240, v239 op_sel_hi:[0,0,0]
	v_exp_f32_e32 v13, v136
	v_exp_f32_e32 v14, v137
	v_exp_f32_e32 v15, v138
	v_exp_f32_e32 v128, v139
	v_cvt_pk_fp8_f32 v3, v1, v10
	v_cvt_pk_fp8_f32 v4, v148, v149
	v_cvt_pk_fp8_f32 v6, v152, v153
	v_cvt_pk_fp8_f32 v7, v13, v14
	v_cvt_pk_fp8_f32 v8, v156, v157
	v_cvt_pk_fp8_f32 v2, v146, v147 op_sel:[0,0,1]
	v_cvt_pk_fp8_f32 v3, v11, v12 op_sel:[0,0,1]
	v_cvt_pk_fp8_f32 v4, v150, v151 op_sel:[0,0,1]
	v_cvt_pk_fp8_f32 v6, v154, v155 op_sel:[0,0,1]
	v_cvt_pk_fp8_f32 v7, v15, v128 op_sel:[0,0,1]
	v_cvt_pk_fp8_f32 v8, v158, v159 op_sel:[0,0,1]
	s_waitcnt lgkmcnt(2)
	v_mfma_scale_f32_32x32x64_f8f6f4 v[160:175], v[194:201], v[184:191], v[160:175], v240, v239 op_sel_hi:[0,0,0]
	v_exp_f32_e32 v129, v140
	v_exp_f32_e32 v130, v141
	v_exp_f32_e32 v131, v142
	v_exp_f32_e32 v132, v143
	v_cvt_pk_fp8_f32 v9, v129, v130
	s_waitcnt lgkmcnt(0)
	v_cvt_pk_fp8_f32 v9, v131, v132 op_sel:[0,0,1]
	v_mfma_scale_f32_32x32x64_f8f6f4 v[112:127], v[246:253], v[184:191], v[112:127], v240, v239 op_sel_hi:[0,0,0]
	s_setprio 0
	s_min_u32 s36, s45, 0x7b
	s_add_i32 s56, s36, 4
	s_lshl_b32 s36, s56, 14
	s_add_i32 s57, s68, 0x0
	s_add_u32 s88, s94, s36
	s_addc_u32 s89, s95, 0
	s_add_i32 m0, s57, 0x8000
	s_lshl_b32 s36, s56, 13
	s_add_u32 s90, s96, s36
	s_addc_u32 s91, s97, 0
	global_load_lds_dwordx4 v192, s[88:89]
	s_mov_b32 m0, s57
	s_nop 0
	global_load_lds_dwordx4 v193, s[90:91]
	ds_read_b128 v[194:197], v254 offset:8192
	ds_read_b128 v[148:151], v254 offset:10240
	ds_read_b128 v[198:201], v255 offset:8192
	ds_read_b128 v[152:155], v255 offset:10240
	ds_read_b128 v[136:139], v254 offset:12288
	ds_read_b128 v[128:131], v254 offset:14336
	ds_read_b128 v[140:143], v255 offset:12288
	ds_read_b128 v[132:135], v255 offset:14336
	v_max_f32_e32 v1, v160, v161
	v_max3_f32 v1, v1, v162, v163
	v_max3_f32 v1, v1, v164, v165
	v_max3_f32 v1, v1, v166, v167
	v_max3_f32 v1, v1, v168, v169
	v_max3_f32 v1, v1, v170, v171
	v_max3_f32 v1, v1, v172, v173
	v_max3_f32 v1, v1, v174, v175
	v_max3_f32 v1, v1, v112, v113
	v_max3_f32 v1, v1, v114, v115
	v_max3_f32 v1, v1, v116, v117
	v_max3_f32 v1, v1, v118, v119
	v_max3_f32 v1, v1, v120, v121
	v_max3_f32 v1, v1, v122, v123
	v_max3_f32 v1, v1, v124, v125
	v_max3_f32 v1, v1, v126, v127
	v_cmp_lt_f32_e32 vcc, s80, v1
	s_cbranch_vccnz .LBB0_384

; __device__ __forceinline__ float max32(const f32x16& p0, const f32x16& p1) {
;   float m = p0[0]; for (int r = 1; r < 16; ++r) m = fmaxf(m, p0[r]); for (int r = 0; r < 16; ++r) m = fmaxf(m, p1[r]);
;   { auto rr = __builtin_amdgcn_permlane32_swap(__float_as_uint(m), __float_as_uint(m), false, false);
;     m = fmaxf(__uint_as_float(rr[0]), __uint_as_float(rr[1])); }
;   return m;
; }
; __device__ __forceinline__ void adjustSM(f32x16& p0, f32x16& p1, f32x16& nm, float& alpha, const float pmax) {
;   alpha = 1.f;
;   if (__builtin_expect(__any(pmax > PSHIFT + THR2), 0)) {
;     const float delta = (pmax > PSHIFT + THR2) ? (pmax - PSHIFT) : 0.f;
;     alpha = __builtin_amdgcn_exp2f(-delta);
;     for (int r = 0; r < 16; ++r) { p0[r] -= delta; p1[r] -= delta; nm[r] -= delta; }
;   }
; }
; __device__ __forceinline__ void partialSM_first(f32x16& p0, f32x16& p1, f32x16& nm) {
;   const float delta = max32(p0, p1) - PSHIFT;
;   for (int r = 0; r < 16; ++r) { p0[r] -= delta; p1[r] -= delta; nm[r] -= delta; }
;   for (int r = 0; r < 16; ++r) p0[r] = __builtin_amdgcn_exp2f(p0[r]);
; }
; __device__ __forceinline__ void finishSM(f32x16& p0, f32x16& p1, v8i& pf) {
;   for (int r = 0; r < 16; ++r) p1[r] = __builtin_amdgcn_exp2f(p1[r]);
; #pragma unroll
;   for (int j = 0; j < 4; ++j) {
;     int a = __builtin_amdgcn_cvt_pk_fp8_f32(p0[4 * j], p0[4 * j + 1], 0, false); a = __builtin_amdgcn_cvt_pk_fp8_f32(p0[4 * j + 2], p0[4 * j + 3], a, true);
;     int b = __builtin_amdgcn_cvt_pk_fp8_f32(p1[4 * j], p1[4 * j + 1], 0, false); b = __builtin_amdgcn_cvt_pk_fp8_f32(p1[4 * j + 2], p1[4 * j + 3], b, true);
;     auto rr = __builtin_amdgcn_permlane32_swap((unsigned)a, (unsigned)b, false, false);
;     pf[2 * j] = (int)rr[0]; pf[2 * j + 1] = (int)rr[1]; }
; }
; __device__ __forceinline__ void qkt(f32x16& p0, f32x16& p1, const f32x16& nm, const char* Ks, const v8i* qr, int ko, int c00, int c01, int c10, int c11) {
;   { const v8i a0 = ld32(Ks + ko + c00, Ks + ko + c01), a1 = ld32(Ks + 4096 + ko + c00, Ks + 4096 + ko + c01);
;     p0 = MFMA8Q(a0, qr[0], nm); p1 = MFMA8Q(a1, qr[0], nm); }
;   { const v8i a0 = ld32(Ks + ko + c10, Ks + ko + c11), a1 = ld32(Ks + 4096 + ko + c10, Ks + 4096 + ko + c11);
;     p0 = MFMA8Q(a0, qr[1], p0); p1 = MFMA8Q(a1, qr[1], p1); }
; }
; __device__ __forceinline__ void pv_load(v8i* vf, const char* Vs, int vo, int e0, int e1) {
; #pragma unroll
.Lc2_374:
	ds_read_b128 v[2:5], v242 offset:57344
	ds_read_b128 v[6:9], v243 offset:57344
	ds_read_b128 v[128:131], v242 offset:61440
	ds_read_b128 v[132:135], v243 offset:61440
	ds_read_b128 v[194:197], v244 offset:57344
	ds_read_b128 v[198:201], v245 offset:57344
	ds_read_b128 v[246:249], v244 offset:61440
	ds_read_b128 v[250:253], v245 offset:61440
	v_exp_f32_e32 v1, v112
	v_exp_f32_e32 v10, v113
	v_exp_f32_e32 v11, v114
	v_exp_f32_e32 v12, v115
	s_waitcnt lgkmcnt(6)
	s_setprio 1
	v_mfma_scale_f32_32x32x64_f8f6f4 v[160:175], v[2:9], v[176:183], v[96:111], v240, v239 op_sel_hi:[0,0,0]
	v_exp_f32_e32 v6, v116
	v_exp_f32_e32 v7, v117
	v_exp_f32_e32 v8, v118
	v_exp_f32_e32 v9, v119
	v_cvt_pk_fp8_f32 v5, v6, v7
	v_cvt_pk_fp8_f32 v3, v1, v10
	v_cvt_pk_fp8_f32 v5, v8, v9 op_sel:[0,0,1]
	s_waitcnt lgkmcnt(4)
	v_mfma_scale_f32_32x32x64_f8f6f4 v[128:143], v[128:135], v[176:183], v[96:111], v240, v239 op_sel_hi:[0,0,0]
	v_exp_f32_e32 v13, v120
	v_exp_f32_e32 v14, v121
	v_exp_f32_e32 v15, v122
	v_exp_f32_e32 v112, v123
	v_cvt_pk_fp8_f32 v2, v144, v145
	v_cvt_pk_fp8_f32 v4, v148, v149
	v_cvt_pk_fp8_f32 v6, v152, v153
	v_cvt_pk_fp8_f32 v7, v13, v14
	v_cvt_pk_fp8_f32 v8, v156, v157
	v_cvt_pk_fp8_f32 v2, v146, v147 op_sel:[0,0,1]
	v_cvt_pk_fp8_f32 v3, v11, v12 op_sel:[0,0,1]
	v_cvt_pk_fp8_f32 v4, v150, v151 op_sel:[0,0,1]
	v_cvt_pk_fp8_f32 v6, v154, v155 op_sel:[0,0,1]
	v_cvt_pk_fp8_f32 v7, v15, v112 op_sel:[0,0,1]
	v_cvt_pk_fp8_f32 v8, v158, v159 op_sel:[0,0,1]
	s_waitcnt lgkmcnt(2)
	v_mfma_scale_f32_32x32x64_f8f6f4 v[160:175], v[194:201], v[184:191], v[160:175], v240, v239 op_sel_hi:[0,0,0]
	v_exp_f32_e32 v113, v124
	v_exp_f32_e32 v114, v125
	v_exp_f32_e32 v1, v126
	v_exp_f32_e32 v10, v127
	v_cvt_pk_fp8_f32 v9, v113, v114
	s_waitcnt lgkmcnt(0)
	v_cvt_pk_fp8_f32 v9, v1, v10 op_sel:[0,0,1]
	v_mfma_scale_f32_32x32x64_f8f6f4 v[128:143], v[246:253], v[184:191], v[128:143], v240, v239 op_sel_hi:[0,0,0]
	s_setprio 0
	s_add_i32 m0, s68, 0xa000
	s_nop 0
	global_load_lds_dwordx4 v192, s[98:99]
	s_add_i32 m0, s68, 0x2000
	s_nop 0
	global_load_lds_dwordx4 v193, s[100:101]
	ds_read_b128 v[194:197], v254 offset:16384
	ds_read_b128 v[148:151], v254 offset:18432
	ds_read_b128 v[198:201], v255 offset:16384
	ds_read_b128 v[152:155], v255 offset:18432
	ds_read_b128 v[120:123], v254 offset:20480
	ds_read_b128 v[112:115], v254 offset:22528
	ds_read_b128 v[124:127], v255 offset:20480
	ds_read_b128 v[116:119], v255 offset:22528
	v_max_f32_e32 v1, v160, v161
	v_max3_f32 v1, v1, v162, v163
	v_max3_f32 v1, v1, v164, v165
	v_max3_f32 v1, v1, v166, v167
	v_max3_f32 v1, v1, v168, v169
	v_max3_f32 v1, v1, v170, v171
	v_max3_f32 v1, v1, v172, v173
	v_max3_f32 v1, v1, v174, v175
	v_max3_f32 v1, v1, v128, v129
	v_max3_f32 v1, v1, v130, v131
	v_max3_f32 v1, v1, v132, v133
	v_max3_f32 v1, v1, v134, v135
	v_max3_f32 v1, v1, v136, v137
	v_max3_f32 v1, v1, v138, v139
	v_max3_f32 v1, v1, v140, v141
	v_max3_f32 v1, v1, v142, v143
	v_cmp_lt_f32_e32 vcc, s80, v1
	s_cbranch_vccnz .Lc2_383

; __device__ __forceinline__ float max32(const f32x16& p0, const f32x16& p1) {
;   float m = p0[0]; for (int r = 1; r < 16; ++r) m = fmaxf(m, p0[r]); for (int r = 0; r < 16; ++r) m = fmaxf(m, p1[r]);
;   { auto rr = __builtin_amdgcn_permlane32_swap(__float_as_uint(m), __float_as_uint(m), false, false);
;     m = fmaxf(__uint_as_float(rr[0]), __uint_as_float(rr[1])); }
;   return m;
; }
; __device__ __forceinline__ void adjustSM(f32x16& p0, f32x16& p1, f32x16& nm, float& alpha, const float pmax) {
;   alpha = 1.f;
;   if (__builtin_expect(__any(pmax > PSHIFT + THR2), 0)) {
;     const float delta = (pmax > PSHIFT + THR2) ? (pmax - PSHIFT) : 0.f;
;     alpha = __builtin_amdgcn_exp2f(-delta);
;     for (int r = 0; r < 16; ++r) { p0[r] -= delta; p1[r] -= delta; nm[r] -= delta; }
;   }
; }
; __device__ __forceinline__ void partialSM_first(f32x16& p0, f32x16& p1, f32x16& nm) {
;   const float delta = max32(p0, p1) - PSHIFT;
;   for (int r = 0; r < 16; ++r) { p0[r] -= delta; p1[r] -= delta; nm[r] -= delta; }
;   for (int r = 0; r < 16; ++r) p0[r] = __builtin_amdgcn_exp2f(p0[r]);
; }
; __device__ __forceinline__ void finishSM(f32x16& p0, f32x16& p1, v8i& pf) {
;   for (int r = 0; r < 16; ++r) p1[r] = __builtin_amdgcn_exp2f(p1[r]);
; #pragma unroll
;   for (int j = 0; j < 4; ++j) {
;     int a = __builtin_amdgcn_cvt_pk_fp8_f32(p0[4 * j], p0[4 * j + 1], 0, false); a = __builtin_amdgcn_cvt_pk_fp8_f32(p0[4 * j + 2], p0[4 * j + 3], a, true);
;     int b = __builtin_amdgcn_cvt_pk_fp8_f32(p1[4 * j], p1[4 * j + 1], 0, false); b = __builtin_amdgcn_cvt_pk_fp8_f32(p1[4 * j + 2], p1[4 * j + 3], b, true);
;     auto rr = __builtin_amdgcn_permlane32_swap((unsigned)a, (unsigned)b, false, false);
;     pf[2 * j] = (int)rr[0]; pf[2 * j + 1] = (int)rr[1]; }
; }
; __device__ __forceinline__ void qkt(f32x16& p0, f32x16& p1, const f32x16& nm, const char* Ks, const v8i* qr, int ko, int c00, int c01, int c10, int c11) {
;   { const v8i a0 = ld32(Ks + ko + c00, Ks + ko + c01), a1 = ld32(Ks + 4096 + ko + c00, Ks + 4096 + ko + c01);
;     p0 = MFMA8Q(a0, qr[0], nm); p1 = MFMA8Q(a1, qr[0], nm); }
;   { const v8i a0 = ld32(Ks + ko + c10, Ks + ko + c11), a1 = ld32(Ks + 4096 + ko + c10, Ks + 4096 + ko + c11);
;     p0 = MFMA8Q(a0, qr[1], p0); p1 = MFMA8Q(a1, qr[1], p1); }
; }
; __device__ __forceinline__ void pv_load(v8i* vf, const char* Vs, int vo, int e0, int e1) {
; #pragma unroll
.Lc2_379:
	s_waitcnt lgkmcnt(0)
	s_barrier
	ds_read_b128 v[2:5], v242 offset:32768
	ds_read_b128 v[6:9], v243 offset:32768
	ds_read_b128 v[112:115], v242 offset:36864
	ds_read_b128 v[116:119], v243 offset:36864
	ds_read_b128 v[194:197], v244 offset:32768
	ds_read_b128 v[198:201], v245 offset:32768
	ds_read_b128 v[246:249], v244 offset:36864
	ds_read_b128 v[250:253], v245 offset:36864
	v_exp_f32_e32 v1, v128
	v_exp_f32_e32 v10, v129
	v_exp_f32_e32 v11, v130
	v_exp_f32_e32 v12, v131
	s_waitcnt lgkmcnt(6)
	s_setprio 1
	v_mfma_scale_f32_32x32x64_f8f6f4 v[160:175], v[2:9], v[176:183], v[96:111], v240, v239 op_sel_hi:[0,0,0]
	v_exp_f32_e32 v6, v132
	v_exp_f32_e32 v7, v133
	v_exp_f32_e32 v8, v134
	v_exp_f32_e32 v9, v135
	v_cvt_pk_fp8_f32 v5, v6, v7
	v_cvt_pk_fp8_f32 v2, v144, v145
	v_cvt_pk_fp8_f32 v5, v8, v9 op_sel:[0,0,1]
	s_waitcnt lgkmcnt(4)
	v_mfma_scale_f32_32x32x64_f8f6f4 v[112:127], v[112:119], v[176:183], v[96:111], v240, v239 op_sel_hi:[0,0,0]
	v_exp_f32_e32 v13, v136
	v_exp_f32_e32 v14, v137
	v_exp_f32_e32 v15, v138
	v_exp_f32_e32 v128, v139
	v_cvt_pk_fp8_f32 v3, v1, v10
	v_cvt_pk_fp8_f32 v4, v148, v149
	v_cvt_pk_fp8_f32 v6, v152, v153
	v_cvt_pk_fp8_f32 v7, v13, v14
	v_cvt_pk_fp8_f32 v8, v156, v157
	v_cvt_pk_fp8_f32 v2, v146, v147 op_sel:[0,0,1]
	v_cvt_pk_fp8_f32 v3, v11, v12 op_sel:[0,0,1]
	v_cvt_pk_fp8_f32 v4, v150, v151 op_sel:[0,0,1]
	v_cvt_pk_fp8_f32 v6, v154, v155 op_sel:[0,0,1]
	v_cvt_pk_fp8_f32 v7, v15, v128 op_sel:[0,0,1]
	v_cvt_pk_fp8_f32 v8, v158, v159 op_sel:[0,0,1]
	s_waitcnt lgkmcnt(2)
	v_mfma_scale_f32_32x32x64_f8f6f4 v[160:175], v[194:201], v[184:191], v[160:175], v240, v239 op_sel_hi:[0,0,0]
	v_exp_f32_e32 v129, v140
	v_exp_f32_e32 v130, v141
	v_exp_f32_e32 v131, v142
	v_exp_f32_e32 v132, v143
	v_cvt_pk_fp8_f32 v9, v129, v130
	s_waitcnt lgkmcnt(0)
	v_cvt_pk_fp8_f32 v9, v131, v132 op_sel:[0,0,1]
	v_mfma_scale_f32_32x32x64_f8f6f4 v[112:127], v[246:253], v[184:191], v[112:127], v240, v239 op_sel_hi:[0,0,0]
	s_setprio 0
	s_min_u32 s36, s45, 0x7b
	s_add_i32 s56, s36, 4
	s_lshl_b32 s36, s56, 14
	s_add_i32 s57, s68, 0x4000
	s_add_u32 s88, s94, s36
	s_addc_u32 s89, s95, 0
	s_add_i32 m0, s57, 0x8000
	s_lshl_b32 s36, s56, 13
	s_add_u32 s90, s96, s36
	s_addc_u32 s91, s97, 0
	global_load_lds_dwordx4 v192, s[88:89]
	s_mov_b32 m0, s57
	s_nop 0
	global_load_lds_dwordx4 v193, s[90:91]
	ds_read_b128 v[194:197], v254 offset:24576
	ds_read_b128 v[148:151], v254 offset:26624
	ds_read_b128 v[198:201], v255 offset:24576
	ds_read_b128 v[152:155], v255 offset:26624
	ds_read_b128 v[136:139], v254 offset:28672
	ds_read_b128 v[128:131], v254 offset:30720
	ds_read_b128 v[140:143], v255 offset:28672
	ds_read_b128 v[132:135], v255 offset:30720
	v_max_f32_e32 v1, v160, v161
	v_max3_f32 v1, v1, v162, v163
	v_max3_f32 v1, v1, v164, v165
	v_max3_f32 v1, v1, v166, v167
	v_max3_f32 v1, v1, v168, v169
	v_max3_f32 v1, v1, v170, v171
	v_max3_f32 v1, v1, v172, v173
	v_max3_f32 v1, v1, v174, v175
	v_max3_f32 v1, v1, v112, v113
	v_max3_f32 v1, v1, v114, v115
	v_max3_f32 v1, v1, v116, v117
	v_max3_f32 v1, v1, v118, v119
	v_max3_f32 v1, v1, v120, v121
	v_max3_f32 v1, v1, v122, v123
	v_max3_f32 v1, v1, v124, v125
	v_max3_f32 v1, v1, v126, v127
	v_cmp_lt_f32_e32 vcc, s80, v1
	s_cbranch_vccnz .Lc2_384

.LgB_375:
	s_waitcnt vmcnt(2) lgkmcnt(0)
	s_barrier
	v_mfma_scale_f32_32x32x64_f8f6f4 v[64:79], v[2:9], v[194:201], v[64:79], v240, v240 op_sel_hi:[0,0,0]
	v_exp_f32_e32 v144, v160
	v_exp_f32_e32 v145, v161
	v_exp_f32_e32 v146, v162
	v_mfma_scale_f32_32x32x64_f8f6f4 v[48:63], v[2:9], v[148:155], v[48:63], v240, v240 op_sel_hi:[0,0,0]
	v_exp_f32_e32 v147, v163
	v_exp_f32_e32 v148, v164
	v_exp_f32_e32 v149, v165
	v_mfma_scale_f32_32x32x64_f8f6f4 v[32:47], v[2:9], v[120:127], v[32:47], v240, v240 op_sel_hi:[0,0,0]
	v_exp_f32_e32 v150, v166
	v_exp_f32_e32 v151, v167
	v_exp_f32_e32 v152, v168
	v_mfma_scale_f32_32x32x64_f8f6f4 v[16:31], v[2:9], v[112:119], v[16:31], v240, v240 op_sel_hi:[0,0,0]
	v_exp_f32_e32 v153, v169
	v_exp_f32_e32 v154, v170
	v_exp_f32_e32 v155, v171
	v_mfma_scale_f32_32x32x64_f8f6f4 v[80:95], v[2:9], v[228:235], v[80:95], v240, v240 op_sel_hi:[0,0,0]
	v_exp_f32_e32 v156, v172
	v_exp_f32_e32 v157, v173
	v_exp_f32_e32 v158, v174
	v_exp_f32_e32 v159, v175
	s_cmp_eq_u32 s93, 0
	s_cbranch_scc1 .LgB_379
	s_mov_b32 s93, 0
	s_and_saveexec_b64 s[56:57], s[4:5]
	ds_write_b32 v236, v1 offset:128
	s_or_b64 exec, exec, s[56:57]
	s_waitcnt lgkmcnt(0)
	v_add_u32_e32 v1, s67, v237
	ds_read_b128 v[2:5], v1 offset:224
	ds_read_b128 v[6:9], v1 offset:192
	ds_read_b128 v[10:13], v1 offset:160
	ds_read_b128 v[112:115], v1 offset:128
	s_waitcnt lgkmcnt(0)
	v_pk_mul_f32 v[76:77], v[76:77], v[2:3]
	v_pk_mul_f32 v[72:73], v[72:73], v[6:7]
	v_pk_mul_f32 v[68:69], v[68:69], v[10:11]
	v_pk_mul_f32 v[78:79], v[78:79], v[4:5]
	v_pk_mul_f32 v[74:75], v[74:75], v[8:9]
	v_pk_mul_f32 v[70:71], v[70:71], v[12:13]
	v_pk_mul_f32 v[66:67], v[66:67], v[114:115]
	v_pk_mul_f32 v[64:65], v[64:65], v[112:113]
	v_pk_mul_f32 v[60:61], v[60:61], v[2:3]
	v_pk_mul_f32 v[56:57], v[56:57], v[6:7]
	v_pk_mul_f32 v[52:53], v[52:53], v[10:11]
	v_pk_mul_f32 v[62:63], v[62:63], v[4:5]
	v_pk_mul_f32 v[58:59], v[58:59], v[8:9]
	v_pk_mul_f32 v[54:55], v[54:55], v[12:13]
	v_pk_mul_f32 v[50:51], v[50:51], v[114:115]
	v_pk_mul_f32 v[48:49], v[48:49], v[112:113]
	v_pk_mul_f32 v[44:45], v[44:45], v[2:3]
	v_pk_mul_f32 v[40:41], v[40:41], v[6:7]
	v_pk_mul_f32 v[36:37], v[36:37], v[10:11]
	v_pk_mul_f32 v[46:47], v[46:47], v[4:5]
	v_pk_mul_f32 v[42:43], v[42:43], v[8:9]
	v_pk_mul_f32 v[38:39], v[38:39], v[12:13]
	v_pk_mul_f32 v[34:35], v[34:35], v[114:115]
	v_pk_mul_f32 v[32:33], v[32:33], v[112:113]
	v_pk_mul_f32 v[28:29], v[28:29], v[2:3]
	v_pk_mul_f32 v[24:25], v[24:25], v[6:7]
	v_pk_mul_f32 v[20:21], v[20:21], v[10:11]
	v_pk_mul_f32 v[30:31], v[30:31], v[4:5]
	v_pk_mul_f32 v[26:27], v[26:27], v[8:9]
	v_pk_mul_f32 v[22:23], v[22:23], v[12:13]
	v_pk_mul_f32 v[18:19], v[18:19], v[114:115]
	v_pk_mul_f32 v[16:17], v[16:17], v[112:113]
	v_pk_mul_f32 v[92:93], v[92:93], v[2:3]
	v_pk_mul_f32 v[88:89], v[88:89], v[6:7]
	v_pk_mul_f32 v[84:85], v[84:85], v[10:11]
	v_pk_mul_f32 v[94:95], v[94:95], v[4:5]
	v_pk_mul_f32 v[90:91], v[90:91], v[8:9]
	v_pk_mul_f32 v[86:87], v[86:87], v[12:13]
	v_pk_mul_f32 v[82:83], v[82:83], v[114:115]
	v_pk_mul_f32 v[80:81], v[80:81], v[112:113]
; __device__ __forceinline__ float max32(const f32x16& p0, const f32x16& p1) {
;   float m = p0[0]; for (int r = 1; r < 16; ++r) m = fmaxf(m, p0[r]); for (int r = 0; r < 16; ++r) m = fmaxf(m, p1[r]);
;   { auto rr = __builtin_amdgcn_permlane32_swap(__float_as_uint(m), __float_as_uint(m), false, false);
;     m = fmaxf(__uint_as_float(rr[0]), __uint_as_float(rr[1])); }
;   return m;
; }
; __device__ __forceinline__ void adjustSM(f32x16& p0, f32x16& p1, f32x16& nm, float& alpha, const float pmax) {
;   alpha = 1.f;
;   if (__builtin_expect(__any(pmax > PSHIFT + THR2), 0)) {
;     const float delta = (pmax > PSHIFT + THR2) ? (pmax - PSHIFT) : 0.f;
;     alpha = __builtin_amdgcn_exp2f(-delta);
;     for (int r = 0; r < 16; ++r) { p0[r] -= delta; p1[r] -= delta; nm[r] -= delta; }
;   }
; }
; __device__ __forceinline__ void partialSM_first(f32x16& p0, f32x16& p1, f32x16& nm) {
;   const float delta = max32(p0, p1) - PSHIFT;
;   for (int r = 0; r < 16; ++r) { p0[r] -= delta; p1[r] -= delta; nm[r] -= delta; }
;   for (int r = 0; r < 16; ++r) p0[r] = __builtin_amdgcn_exp2f(p0[r]);
; }
; __device__ __forceinline__ void finishSM(f32x16& p0, f32x16& p1, v8i& pf) {
;   for (int r = 0; r < 16; ++r) p1[r] = __builtin_amdgcn_exp2f(p1[r]);
; #pragma unroll
;   for (int j = 0; j < 4; ++j) {
;     int a = __builtin_amdgcn_cvt_pk_fp8_f32(p0[4 * j], p0[4 * j + 1], 0, false); a = __builtin_amdgcn_cvt_pk_fp8_f32(p0[4 * j + 2], p0[4 * j + 3], a, true);
;     int b = __builtin_amdgcn_cvt_pk_fp8_f32(p1[4 * j], p1[4 * j + 1], 0, false); b = __builtin_amdgcn_cvt_pk_fp8_f32(p1[4 * j + 2], p1[4 * j + 3], b, true);
;     auto rr = __builtin_amdgcn_permlane32_swap((unsigned)a, (unsigned)b, false, false);
;     pf[2 * j] = (int)rr[0]; pf[2 * j + 1] = (int)rr[1]; }
; }
; __device__ __forceinline__ void qkt(f32x16& p0, f32x16& p1, const f32x16& nm, const char* Ks, const v8i* qr, int ko, int c00, int c01, int c10, int c11) {
;   { const v8i a0 = ld32(Ks + ko + c00, Ks + ko + c01), a1 = ld32(Ks + 4096 + ko + c00, Ks + 4096 + ko + c01);
;     p0 = MFMA8Q(a0, qr[0], nm); p1 = MFMA8Q(a1, qr[0], nm); }
;   { const v8i a0 = ld32(Ks + ko + c10, Ks + ko + c11), a1 = ld32(Ks + 4096 + ko + c10, Ks + 4096 + ko + c11);
;     p0 = MFMA8Q(a0, qr[1], p0); p1 = MFMA8Q(a1, qr[1], p1); }
; }
; __device__ __forceinline__ void pv_load(v8i* vf, const char* Vs, int vo, int e0, int e1) {
; #pragma unroll
.LgB_379:
	ds_read_b128 v[2:5], v242 offset:49152
	ds_read_b128 v[6:9], v243 offset:49152
	ds_read_b128 v[112:115], v242 offset:53248
	ds_read_b128 v[116:119], v243 offset:53248
	ds_read_b128 v[194:197], v244 offset:49152
	ds_read_b128 v[198:201], v245 offset:49152
	ds_read_b128 v[246:249], v244 offset:53248
	ds_read_b128 v[250:253], v245 offset:53248
	v_exp_f32_e32 v1, v128
	v_exp_f32_e32 v10, v129
	v_exp_f32_e32 v11, v130
	v_exp_f32_e32 v12, v131
	s_waitcnt lgkmcnt(6)
	s_setprio 1
	v_mfma_scale_f32_32x32x64_f8f6f4 v[160:175], v[2:9], v[176:183], v[96:111], v240, v239 op_sel_hi:[0,0,0]
	v_exp_f32_e32 v6, v132
	v_exp_f32_e32 v7, v133
	v_exp_f32_e32 v8, v134
	v_exp_f32_e32 v9, v135
	v_cvt_pk_fp8_f32 v5, v6, v7
	v_cvt_pk_fp8_f32 v2, v144, v145
	v_cvt_pk_fp8_f32 v5, v8, v9 op_sel:[0,0,1]
	s_waitcnt lgkmcnt(4)
	v_mfma_scale_f32_32x32x64_f8f6f4 v[112:127], v[112:119], v[176:183], v[96:111], v240, v239 op_sel_hi:[0,0,0]
	v_exp_f32_e32 v13, v136
	v_exp_f32_e32 v14, v137
	v_exp_f32_e32 v15, v138
	v_exp_f32_e32 v128, v139
	v_cvt_pk_fp8_f32 v3, v1, v10
	v_cvt_pk_fp8_f32 v4, v148, v149
	v_cvt_pk_fp8_f32 v6, v152, v153
	v_cvt_pk_fp8_f32 v7, v13, v14
	v_cvt_pk_fp8_f32 v8, v156, v157
	v_cvt_pk_fp8_f32 v2, v146, v147 op_sel:[0,0,1]
	v_cvt_pk_fp8_f32 v3, v11, v12 op_sel:[0,0,1]
	v_cvt_pk_fp8_f32 v4, v150, v151 op_sel:[0,0,1]
	v_cvt_pk_fp8_f32 v6, v154, v155 op_sel:[0,0,1]
	v_cvt_pk_fp8_f32 v7, v15, v128 op_sel:[0,0,1]
	v_cvt_pk_fp8_f32 v8, v158, v159 op_sel:[0,0,1]
	s_waitcnt lgkmcnt(2)
	v_mfma_scale_f32_32x32x64_f8f6f4 v[160:175], v[194:201], v[184:191], v[160:175], v240, v239 op_sel_hi:[0,0,0]
	v_exp_f32_e32 v129, v140
	v_exp_f32_e32 v130, v141
	v_exp_f32_e32 v131, v142
	v_exp_f32_e32 v132, v143
	v_cvt_pk_fp8_f32 v9, v129, v130
	s_waitcnt lgkmcnt(0)
	v_cvt_pk_fp8_f32 v9, v131, v132 op_sel:[0,0,1]
	v_mfma_scale_f32_32x32x64_f8f6f4 v[112:127], v[246:253], v[184:191], v[112:127], v240, v239 op_sel_hi:[0,0,0]
	s_setprio 0
	s_min_u32 s36, s45, 0x7b
	s_add_i32 s56, s36, 4
	s_lshl_b32 s36, s56, 14
	s_add_i32 s57, s68, 0x0
	s_add_u32 s88, s94, s36
	s_addc_u32 s89, s95, 0
	s_add_i32 m0, s57, 0x8000
	s_lshl_b32 s36, s56, 13
	s_add_u32 s90, s96, s36
	s_addc_u32 s91, s97, 0
	global_load_lds_dwordx4 v192, s[88:89]
	s_mov_b32 m0, s57
	s_nop 0
	global_load_lds_dwordx4 v193, s[90:91]
	ds_read_b128 v[194:197], v254 offset:8192
	ds_read_b128 v[148:151], v254 offset:10240
	ds_read_b128 v[198:201], v255 offset:8192
	ds_read_b128 v[152:155], v255 offset:10240
	ds_read_b128 v[136:139], v254 offset:12288
	ds_read_b128 v[128:131], v254 offset:14336
	ds_read_b128 v[140:143], v255 offset:12288
	ds_read_b128 v[132:135], v255 offset:14336
	v_max_f32_e32 v1, v160, v161
	v_max3_f32 v1, v1, v162, v163
	v_max3_f32 v1, v1, v164, v165
	v_max3_f32 v1, v1, v166, v167
	v_max3_f32 v1, v1, v168, v169
	v_max3_f32 v1, v1, v170, v171
	v_max3_f32 v1, v1, v172, v173
	v_max3_f32 v1, v1, v174, v175
	v_max3_f32 v1, v1, v112, v113
	v_max3_f32 v1, v1, v114, v115
	v_max3_f32 v1, v1, v116, v117
	v_max3_f32 v1, v1, v118, v119
	v_max3_f32 v1, v1, v120, v121
	v_max3_f32 v1, v1, v122, v123
	v_max3_f32 v1, v1, v124, v125
	v_max3_f32 v1, v1, v126, v127
	v_cmp_lt_f32_e32 vcc, s80, v1
	s_cbranch_vccnz .LgB_384
.LgB_380:
	s_waitcnt vmcnt(2) lgkmcnt(0)
	s_barrier
	v_mfma_scale_f32_32x32x64_f8f6f4 v[64:79], v[2:9], v[194:201], v[64:79], v240, v240 op_sel_hi:[0,0,0]
	v_exp_f32_e32 v144, v160
	v_exp_f32_e32 v145, v161
	v_exp_f32_e32 v146, v162
	v_mfma_scale_f32_32x32x64_f8f6f4 v[48:63], v[2:9], v[148:155], v[48:63], v240, v240 op_sel_hi:[0,0,0]
	v_exp_f32_e32 v147, v163
	v_exp_f32_e32 v148, v164
	v_exp_f32_e32 v149, v165
	v_mfma_scale_f32_32x32x64_f8f6f4 v[32:47], v[2:9], v[136:143], v[32:47], v240, v240 op_sel_hi:[0,0,0]
	v_exp_f32_e32 v150, v166
	v_exp_f32_e32 v151, v167
	v_exp_f32_e32 v152, v168
	v_mfma_scale_f32_32x32x64_f8f6f4 v[16:31], v[2:9], v[128:135], v[16:31], v240, v240 op_sel_hi:[0,0,0]
	v_exp_f32_e32 v153, v169
	v_exp_f32_e32 v154, v170
	v_exp_f32_e32 v155, v171
	v_mfma_scale_f32_32x32x64_f8f6f4 v[80:95], v[2:9], v[228:235], v[80:95], v240, v240 op_sel_hi:[0,0,0]
	v_exp_f32_e32 v156, v172
	v_exp_f32_e32 v157, v173
	v_exp_f32_e32 v158, v174
	v_exp_f32_e32 v159, v175
	s_cmp_eq_u32 s93, 0
	s_cbranch_scc1 .LgB_373
	s_mov_b32 s93, 0
	s_and_saveexec_b64 s[56:57], s[4:5]
	s_cbranch_execz .LgB_372
	ds_write_b32 v236, v1 offset:128
	s_branch .LgB_372

; __device__ __forceinline__ float max32(const f32x16& p0, const f32x16& p1) {
;   float m = p0[0]; for (int r = 1; r < 16; ++r) m = fmaxf(m, p0[r]); for (int r = 0; r < 16; ++r) m = fmaxf(m, p1[r]);
;   { auto rr = __builtin_amdgcn_permlane32_swap(__float_as_uint(m), __float_as_uint(m), false, false);
;     m = fmaxf(__uint_as_float(rr[0]), __uint_as_float(rr[1])); }
;   return m;
; }
; __device__ __forceinline__ void adjustSM(f32x16& p0, f32x16& p1, f32x16& nm, float& alpha, const float pmax) {
;   alpha = 1.f;
;   if (__builtin_expect(__any(pmax > PSHIFT + THR2), 0)) {
;     const float delta = (pmax > PSHIFT + THR2) ? (pmax - PSHIFT) : 0.f;
;     alpha = __builtin_amdgcn_exp2f(-delta);
;     for (int r = 0; r < 16; ++r) { p0[r] -= delta; p1[r] -= delta; nm[r] -= delta; }
;   }
; }
; __device__ __forceinline__ void partialSM_first(f32x16& p0, f32x16& p1, f32x16& nm) {
;   const float delta = max32(p0, p1) - PSHIFT;
;   for (int r = 0; r < 16; ++r) { p0[r] -= delta; p1[r] -= delta; nm[r] -= delta; }
;   for (int r = 0; r < 16; ++r) p0[r] = __builtin_amdgcn_exp2f(p0[r]);
; }
; __device__ __forceinline__ void finishSM(f32x16& p0, f32x16& p1, v8i& pf) {
;   for (int r = 0; r < 16; ++r) p1[r] = __builtin_amdgcn_exp2f(p1[r]);
; #pragma unroll
;   for (int j = 0; j < 4; ++j) {
;     int a = __builtin_amdgcn_cvt_pk_fp8_f32(p0[4 * j], p0[4 * j + 1], 0, false); a = __builtin_amdgcn_cvt_pk_fp8_f32(p0[4 * j + 2], p0[4 * j + 3], a, true);
;     int b = __builtin_amdgcn_cvt_pk_fp8_f32(p1[4 * j], p1[4 * j + 1], 0, false); b = __builtin_amdgcn_cvt_pk_fp8_f32(p1[4 * j + 2], p1[4 * j + 3], b, true);
;     auto rr = __builtin_amdgcn_permlane32_swap((unsigned)a, (unsigned)b, false, false);
;     pf[2 * j] = (int)rr[0]; pf[2 * j + 1] = (int)rr[1]; }
; }
; __device__ __forceinline__ void qkt(f32x16& p0, f32x16& p1, const f32x16& nm, const char* Ks, const v8i* qr, int ko, int c00, int c01, int c10, int c11) {
;   { const v8i a0 = ld32(Ks + ko + c00, Ks + ko + c01), a1 = ld32(Ks + 4096 + ko + c00, Ks + 4096 + ko + c01);
;     p0 = MFMA8Q(a0, qr[0], nm); p1 = MFMA8Q(a1, qr[0], nm); }
;   { const v8i a0 = ld32(Ks + ko + c10, Ks + ko + c11), a1 = ld32(Ks + 4096 + ko + c10, Ks + 4096 + ko + c11);
;     p0 = MFMA8Q(a0, qr[1], p0); p1 = MFMA8Q(a1, qr[1], p1); }
; }
; __device__ __forceinline__ void pv_load(v8i* vf, const char* Vs, int vo, int e0, int e1) {
; #pragma unroll
.LgBc2_379:
	ds_read_b128 v[2:5], v242 offset:32768
	ds_read_b128 v[6:9], v243 offset:32768
	ds_read_b128 v[112:115], v242 offset:36864
	ds_read_b128 v[116:119], v243 offset:36864
	ds_read_b128 v[194:197], v244 offset:32768
	ds_read_b128 v[198:201], v245 offset:32768
	ds_read_b128 v[246:249], v244 offset:36864
	ds_read_b128 v[250:253], v245 offset:36864
	v_exp_f32_e32 v1, v128
	v_exp_f32_e32 v10, v129
	v_exp_f32_e32 v11, v130
	v_exp_f32_e32 v12, v131
	s_waitcnt lgkmcnt(6)
	s_setprio 1
	v_mfma_scale_f32_32x32x64_f8f6f4 v[160:175], v[2:9], v[176:183], v[96:111], v240, v239 op_sel_hi:[0,0,0]
	v_exp_f32_e32 v6, v132
	v_exp_f32_e32 v7, v133
	v_exp_f32_e32 v8, v134
	v_exp_f32_e32 v9, v135
	v_cvt_pk_fp8_f32 v5, v6, v7
	v_cvt_pk_fp8_f32 v2, v144, v145
	v_cvt_pk_fp8_f32 v5, v8, v9 op_sel:[0,0,1]
	s_waitcnt lgkmcnt(4)
	v_mfma_scale_f32_32x32x64_f8f6f4 v[112:127], v[112:119], v[176:183], v[96:111], v240, v239 op_sel_hi:[0,0,0]
	v_exp_f32_e32 v13, v136
	v_exp_f32_e32 v14, v137
	v_exp_f32_e32 v15, v138
	v_exp_f32_e32 v128, v139
	v_cvt_pk_fp8_f32 v3, v1, v10
	v_cvt_pk_fp8_f32 v4, v148, v149
	v_cvt_pk_fp8_f32 v6, v152, v153
	v_cvt_pk_fp8_f32 v7, v13, v14
	v_cvt_pk_fp8_f32 v8, v156, v157
	v_cvt_pk_fp8_f32 v2, v146, v147 op_sel:[0,0,1]
	v_cvt_pk_fp8_f32 v3, v11, v12 op_sel:[0,0,1]
	v_cvt_pk_fp8_f32 v4, v150, v151 op_sel:[0,0,1]
	v_cvt_pk_fp8_f32 v6, v154, v155 op_sel:[0,0,1]
	v_cvt_pk_fp8_f32 v7, v15, v128 op_sel:[0,0,1]
	v_cvt_pk_fp8_f32 v8, v158, v159 op_sel:[0,0,1]
	s_waitcnt lgkmcnt(2)
	v_mfma_scale_f32_32x32x64_f8f6f4 v[160:175], v[194:201], v[184:191], v[160:175], v240, v239 op_sel_hi:[0,0,0]
	v_exp_f32_e32 v129, v140
	v_exp_f32_e32 v130, v141
	v_exp_f32_e32 v131, v142
	v_exp_f32_e32 v132, v143
	v_cvt_pk_fp8_f32 v9, v129, v130
	s_waitcnt lgkmcnt(0)
	v_cvt_pk_fp8_f32 v9, v131, v132 op_sel:[0,0,1]
	v_mfma_scale_f32_32x32x64_f8f6f4 v[112:127], v[246:253], v[184:191], v[112:127], v240, v239 op_sel_hi:[0,0,0]
	s_setprio 0
	s_min_u32 s36, s45, 0x7b
	s_add_i32 s56, s36, 4
	s_lshl_b32 s36, s56, 14
	s_add_i32 s57, s68, 0x4000
	s_add_u32 s88, s94, s36
	s_addc_u32 s89, s95, 0
	s_add_i32 m0, s57, 0x8000
	s_lshl_b32 s36, s56, 13
	s_add_u32 s90, s96, s36
	s_addc_u32 s91, s97, 0
	global_load_lds_dwordx4 v192, s[88:89]
	s_mov_b32 m0, s57
	s_nop 0
	global_load_lds_dwordx4 v193, s[90:91]
	ds_read_b128 v[194:197], v254 offset:24576
	ds_read_b128 v[148:151], v254 offset:26624
	ds_read_b128 v[198:201], v255 offset:24576
	ds_read_b128 v[152:155], v255 offset:26624
	ds_read_b128 v[136:139], v254 offset:28672
	ds_read_b128 v[128:131], v254 offset:30720
	ds_read_b128 v[140:143], v255 offset:28672
	ds_read_b128 v[132:135], v255 offset:30720
	v_max_f32_e32 v1, v160, v161
	v_max3_f32 v1, v1, v162, v163
	v_max3_f32 v1, v1, v164, v165
	v_max3_f32 v1, v1, v166, v167
	v_max3_f32 v1, v1, v168, v169
	v_max3_f32 v1, v1, v170, v171
	v_max3_f32 v1, v1, v172, v173
	v_max3_f32 v1, v1, v174, v175
	v_max3_f32 v1, v1, v112, v113
	v_max3_f32 v1, v1, v114, v115
	v_max3_f32 v1, v1, v116, v117
	v_max3_f32 v1, v1, v118, v119
	v_max3_f32 v1, v1, v120, v121
	v_max3_f32 v1, v1, v122, v123
	v_max3_f32 v1, v1, v124, v125
	v_max3_f32 v1, v1, v126, v127
	v_cmp_lt_f32_e32 vcc, s80, v1
	s_cbranch_vccnz .LgBc2_384

; #define PG8_STAGE(bufoff, gbase, voff) do { _Pragma("unroll") for (int _i = 0; _i < 2; ++_i) \
;         __builtin_amdgcn_global_load_lds((const unsigned*)((const char*)(gbase) + (voff)[_i]), (LAS unsigned*)(lds + (bufoff) + ldsw + _i * 8192), 16, 0, 0); } while (0)
; #define PG8_LDA(dst, b, h) do { _Pragma("unroll") for (int m = 0; m < 4; ++m) _Pragma("unroll") for (int k = 0; k < 2; ++k) dst[m][k] = *(const LAS bf16x8*)(lds + PG8_SA(b, h) + aoff + m * 2048 + k * 1024); } while (0)
; #define PG8_LDB(dst, b, h) do { _Pragma("unroll") for (int n = 0; n < 2; ++n) _Pragma("unroll") for (int k = 0; k < 2; ++k) dst[n][k] = *(const LAS bf16x8*)(lds + PG8_SB(b, h) + boff + n * 2048 + k * 1024); } while (0)
; #define PG8_MMA(ai, bj, At, Bt) do { __builtin_amdgcn_s_setprio(1); _Pragma("unroll") for (int m = 0; m < 4; ++m) _Pragma("unroll") for (int n = 0; n < 2; ++n) _Pragma("unroll") for (int k = 0; k < 2; ++k) \
;         acc[ai][bj][m][n] = __builtin_amdgcn_mfma_f32_16x16x32_bf16(Bt[n][k], At[m][k], acc[ai][bj][m][n], 0, 0, 0); __builtin_amdgcn_s_setprio(0); } while (0)
; #define PG8_WAIT_V(n) asm volatile("s_waitcnt vmcnt(" #n ")" ::: "memory")
; #define PG8_WAIT_L(n) asm volatile("s_waitcnt lgkmcnt(" #n ")" ::: "memory")
; #define PG8_BAR __builtin_amdgcn_s_barrier()
; #define PG8_SCHED __builtin_amdgcn_sched_barrier(0)
; template <class Epi, class Sched>
; __device__ __forceinline__ void gemm_phase(LAS unsigned char* lds, const Gemm g, const Sched& S, const Epi& E, const int wid) {
;     ...
;             const bool last = (t == nt - 2);
;             const char* a1 = cA + (size_t)(t + 1) * kstep;
;             const char* a2 = last ? nA : cA + (size_t)(t + 2) * kstep; const char* b2 = last ? nB : cB + (size_t)(t + 2) * kstep;
;             const char* a3 = a2 + kstep; const char* b3 = b2 + kstep;
;             PG8_LDB(B0, 0, 0); PG8_LDB(B1, 0, 1); PG8_SCHED; PG8_LDA(At, 0, 0); PG8_STAGE(PG8_SA(1, 1), a1 + hstepA, voffA);
;             PG8_WAIT_V(8); PG8_WAIT_L(0); PG8_BAR; PG8_MMA(0, 0, At, B0); PG8_MMA(0, 1, At, B1); PG8_BAR; PG8_SCHED;
;             PG8_LDA(At, 0, 1); PG8_STAGE(PG8_SB(0, 0), b2, voffB); PG8_STAGE(PG8_SB(0, 1), b2 + hstepB, voffB); PG8_STAGE(PG8_SA(0, 0), a2, voffA);
;             PG8_WAIT_V(8); PG8_WAIT_L(0); PG8_BAR; PG8_MMA(1, 0, At, B0); PG8_MMA(1, 1, At, B1); PG8_BAR; PG8_SCHED;
.LBB0_459:
	ds_read_b128 v[72:75], v199
	ds_read_b128 v[80:83], v199 offset:1024
	ds_read_b128 v[84:87], v199 offset:2048
	ds_read_b128 v[92:95], v199 offset:3072
	ds_read_b128 v[144:147], v200
	ds_read_b128 v[148:151], v200 offset:1024
	ds_read_b128 v[152:155], v200 offset:2048
	ds_read_b128 v[156:159], v200 offset:3072
	s_add_u32 s56, s54, 0xfffc0080
	s_addc_u32 s57, s55, -1
	s_cmp_eq_u32 s88, 12
	s_cselect_b32 s59, s45, s57
	s_cselect_b32 s58, s51, s56
	s_cselect_b32 s57, s43, s87
	s_cselect_b32 s56, s85, s86
	v_lshl_add_u64 v[210:211], s[54:55], 0, v[164:165]
	s_add_i32 m0, s53, 0xc000
	ds_read_b128 v[172:175], v201
	ds_read_b128 v[176:179], v201 offset:1024
	ds_read_b128 v[180:183], v201 offset:2048
	ds_read_b128 v[184:187], v201 offset:3072
	ds_read_b128 v[188:191], v201 offset:4096
	ds_read_b128 v[192:195], v201 offset:5120
	ds_read_b128 v[202:205], v201 offset:6144
	ds_read_b128 v[206:209], v201 offset:7168
	global_load_lds_dwordx4 v[210:211], off
	v_lshl_add_u64 v[210:211], s[54:55], 0, v[166:167]
	s_add_i32 m0, s53, 0xe000
	s_nop 0
	global_load_lds_dwordx4 v[210:211], off
	s_waitcnt vmcnt(8)
	s_waitcnt lgkmcnt(0)
	s_barrier
	s_setprio 1
	v_mfma_f32_16x16x32_bf16 v[140:143], v[72:75], v[172:175], v[140:143]
	v_mfma_f32_16x16x32_bf16 v[136:139], v[84:87], v[172:175], v[136:139]
	v_mfma_f32_16x16x32_bf16 v[124:127], v[72:75], v[180:183], v[124:127]
	v_mfma_f32_16x16x32_bf16 v[120:123], v[84:87], v[180:183], v[120:123]
	v_mfma_f32_16x16x32_bf16 v[108:111], v[72:75], v[188:191], v[108:111]
	v_mfma_f32_16x16x32_bf16 v[104:107], v[84:87], v[188:191], v[104:107]
	v_mfma_f32_16x16x32_bf16 v[88:91], v[72:75], v[202:205], v[88:91]
	v_mfma_f32_16x16x32_bf16 v[76:79], v[84:87], v[202:205], v[76:79]
	v_mfma_f32_16x16x32_bf16 v[140:143], v[80:83], v[176:179], v[140:143]
	v_mfma_f32_16x16x32_bf16 v[136:139], v[92:95], v[176:179], v[136:139]
	v_mfma_f32_16x16x32_bf16 v[124:127], v[80:83], v[184:187], v[124:127]
	v_mfma_f32_16x16x32_bf16 v[120:123], v[92:95], v[184:187], v[120:123]
	v_mfma_f32_16x16x32_bf16 v[108:111], v[80:83], v[192:195], v[108:111]
	v_mfma_f32_16x16x32_bf16 v[104:107], v[92:95], v[192:195], v[104:107]
	v_mfma_f32_16x16x32_bf16 v[88:91], v[80:83], v[206:209], v[88:91]
	v_mfma_f32_16x16x32_bf16 v[76:79], v[92:95], v[206:209], v[76:79]
	v_mfma_f32_16x16x32_bf16 v[132:135], v[144:147], v[172:175], v[132:135]
	v_mfma_f32_16x16x32_bf16 v[128:131], v[152:155], v[172:175], v[128:131]
	v_mfma_f32_16x16x32_bf16 v[116:119], v[144:147], v[180:183], v[116:119]
	v_mfma_f32_16x16x32_bf16 v[112:115], v[152:155], v[180:183], v[112:115]
	v_mfma_f32_16x16x32_bf16 v[100:103], v[144:147], v[188:191], v[100:103]
	v_mfma_f32_16x16x32_bf16 v[96:99], v[152:155], v[188:191], v[96:99]
	v_mfma_f32_16x16x32_bf16 v[68:71], v[144:147], v[202:205], v[68:71]
	v_mfma_f32_16x16x32_bf16 v[64:67], v[152:155], v[202:205], v[64:67]
	v_mfma_f32_16x16x32_bf16 v[132:135], v[148:151], v[176:179], v[132:135]
	v_mfma_f32_16x16x32_bf16 v[128:131], v[156:159], v[176:179], v[128:131]
	v_mfma_f32_16x16x32_bf16 v[116:119], v[148:151], v[184:187], v[116:119]
	v_mfma_f32_16x16x32_bf16 v[112:115], v[156:159], v[184:187], v[112:115]
	v_mfma_f32_16x16x32_bf16 v[100:103], v[148:151], v[192:195], v[100:103]
	v_mfma_f32_16x16x32_bf16 v[96:99], v[156:159], v[192:195], v[96:99]
	v_mfma_f32_16x16x32_bf16 v[68:71], v[148:151], v[206:209], v[68:71]
	v_mfma_f32_16x16x32_bf16 v[64:67], v[156:159], v[206:209], v[64:67]
	s_setprio 0
	s_barrier
	s_add_i32 s89, s78, s63
	v_lshl_add_u64 v[210:211], s[56:57], 0, v[160:161]
	s_mov_b32 m0, s89
	ds_read_b128 v[172:175], v201 offset:16384
	ds_read_b128 v[176:179], v201 offset:17408
	ds_read_b128 v[180:183], v201 offset:18432
	ds_read_b128 v[184:187], v201 offset:19456
	ds_read_b128 v[188:191], v201 offset:20480
	ds_read_b128 v[192:195], v201 offset:21504
	ds_read_b128 v[202:205], v201 offset:22528
	ds_read_b128 v[206:209], v201 offset:23552
	global_load_lds_dwordx4 v[210:211], off
	s_add_i32 m0, s89, 0x2000
	s_add_u32 s90, s56, 0x40000
	v_lshl_add_u64 v[212:213], s[56:57], 0, v[162:163]
	s_addc_u32 s91, s57, 0
	s_add_i32 s89, s79, s63
	global_load_lds_dwordx4 v[212:213], off
	v_lshl_add_u64 v[214:215], s[90:91], 0, v[160:161]
	s_mov_b32 m0, s89
	v_lshl_add_u64 v[216:217], s[58:59], 0, v[162:163]
	global_load_lds_dwordx4 v[214:215], off
	v_lshl_add_u64 v[214:215], s[90:91], 0, v[162:163]
	s_add_i32 m0, s89, 0x2000
	s_nop 0
	global_load_lds_dwordx4 v[214:215], off
	v_lshl_add_u64 v[214:215], s[58:59], 0, v[160:161]
	s_mov_b32 m0, s53
	s_nop 0
	global_load_lds_dwordx4 v[214:215], off
	s_mov_b32 m0, s64
	s_nop 0
	global_load_lds_dwordx4 v[216:217], off
	s_waitcnt vmcnt(8)
	s_waitcnt lgkmcnt(0)
	s_barrier
; #define PG8_STAGE(bufoff, gbase, voff) do { _Pragma("unroll") for (int _i = 0; _i < 2; ++_i) \
;         __builtin_amdgcn_global_load_lds((const unsigned*)((const char*)(gbase) + (voff)[_i]), (LAS unsigned*)(lds + (bufoff) + ldsw + _i * 8192), 16, 0, 0); } while (0)
; #define PG8_LDA(dst, b, h) do { _Pragma("unroll") for (int m = 0; m < 4; ++m) _Pragma("unroll") for (int k = 0; k < 2; ++k) dst[m][k] = *(const LAS bf16x8*)(lds + PG8_SA(b, h) + aoff + m * 2048 + k * 1024); } while (0)
; #define PG8_LDB(dst, b, h) do { _Pragma("unroll") for (int n = 0; n < 2; ++n) _Pragma("unroll") for (int k = 0; k < 2; ++k) dst[n][k] = *(const LAS bf16x8*)(lds + PG8_SB(b, h) + boff + n * 2048 + k * 1024); } while (0)
; #define PG8_MMA(ai, bj, At, Bt) do { __builtin_amdgcn_s_setprio(1); _Pragma("unroll") for (int m = 0; m < 4; ++m) _Pragma("unroll") for (int n = 0; n < 2; ++n) _Pragma("unroll") for (int k = 0; k < 2; ++k) \
;         acc[ai][bj][m][n] = __builtin_amdgcn_mfma_f32_16x16x32_bf16(Bt[n][k], At[m][k], acc[ai][bj][m][n], 0, 0, 0); __builtin_amdgcn_s_setprio(0); } while (0)
; #define PG8_WAIT_V(n) asm volatile("s_waitcnt vmcnt(" #n ")" ::: "memory")
; #define PG8_WAIT_L(n) asm volatile("s_waitcnt lgkmcnt(" #n ")" ::: "memory")
; #define PG8_BAR __builtin_amdgcn_s_barrier()
; #define PG8_SCHED __builtin_amdgcn_sched_barrier(0)
; template <class Epi, class Sched>
; __device__ __forceinline__ void gemm_phase(LAS unsigned char* lds, const Gemm g, const Sched& S, const Epi& E, const int wid) {
;     ...
;             PG8_WAIT_V(8); PG8_WAIT_L(0); PG8_BAR; PG8_MMA(1, 0, At, B0); PG8_MMA(1, 1, At, B1); PG8_BAR; PG8_SCHED;
;             PG8_LDB(B0, 1, 0); PG8_LDB(B1, 1, 1); PG8_SCHED; PG8_LDA(At, 1, 0); PG8_STAGE(PG8_SA(0, 1), a2 + hstepA, voffA);
;             PG8_WAIT_V(8); PG8_WAIT_L(0); PG8_BAR; PG8_MMA(0, 0, At, B0); PG8_MMA(0, 1, At, B1); PG8_BAR; PG8_SCHED;
	s_setprio 1
	v_mfma_f32_16x16x32_bf16 v[60:63], v[72:75], v[172:175], v[60:63]
	v_mfma_f32_16x16x32_bf16 v[56:59], v[84:87], v[172:175], v[56:59]
	v_mfma_f32_16x16x32_bf16 v[44:47], v[72:75], v[180:183], v[44:47]
	v_mfma_f32_16x16x32_bf16 v[40:43], v[84:87], v[180:183], v[40:43]
	v_mfma_f32_16x16x32_bf16 v[28:31], v[72:75], v[188:191], v[28:31]
	v_mfma_f32_16x16x32_bf16 v[24:27], v[84:87], v[188:191], v[24:27]
	v_mfma_f32_16x16x32_bf16 v[12:15], v[72:75], v[202:205], v[12:15]
	v_mfma_f32_16x16x32_bf16 v[8:11], v[84:87], v[202:205], v[8:11]
	v_mfma_f32_16x16x32_bf16 v[60:63], v[80:83], v[176:179], v[60:63]
	v_mfma_f32_16x16x32_bf16 v[56:59], v[92:95], v[176:179], v[56:59]
	v_mfma_f32_16x16x32_bf16 v[44:47], v[80:83], v[184:187], v[44:47]
	v_mfma_f32_16x16x32_bf16 v[40:43], v[92:95], v[184:187], v[40:43]
	v_mfma_f32_16x16x32_bf16 v[28:31], v[80:83], v[192:195], v[28:31]
	v_mfma_f32_16x16x32_bf16 v[24:27], v[92:95], v[192:195], v[24:27]
	v_mfma_f32_16x16x32_bf16 v[12:15], v[80:83], v[206:209], v[12:15]
	v_mfma_f32_16x16x32_bf16 v[8:11], v[92:95], v[206:209], v[8:11]
	v_mfma_f32_16x16x32_bf16 v[52:55], v[144:147], v[172:175], v[52:55]
	v_mfma_f32_16x16x32_bf16 v[48:51], v[152:155], v[172:175], v[48:51]
	v_mfma_f32_16x16x32_bf16 v[36:39], v[144:147], v[180:183], v[36:39]
	v_mfma_f32_16x16x32_bf16 v[32:35], v[152:155], v[180:183], v[32:35]
	v_mfma_f32_16x16x32_bf16 v[20:23], v[144:147], v[188:191], v[20:23]
	v_mfma_f32_16x16x32_bf16 v[16:19], v[152:155], v[188:191], v[16:19]
	v_mfma_f32_16x16x32_bf16 v[4:7], v[144:147], v[202:205], v[4:7]
	v_mfma_f32_16x16x32_bf16 v[0:3], v[152:155], v[202:205], v[0:3]
	v_mfma_f32_16x16x32_bf16 v[52:55], v[148:151], v[176:179], v[52:55]
	v_mfma_f32_16x16x32_bf16 v[48:51], v[156:159], v[176:179], v[48:51]
	v_mfma_f32_16x16x32_bf16 v[36:39], v[148:151], v[184:187], v[36:39]
	v_mfma_f32_16x16x32_bf16 v[32:35], v[156:159], v[184:187], v[32:35]
	v_mfma_f32_16x16x32_bf16 v[20:23], v[148:151], v[192:195], v[20:23]
	v_mfma_f32_16x16x32_bf16 v[16:19], v[156:159], v[192:195], v[16:19]
	v_mfma_f32_16x16x32_bf16 v[4:7], v[148:151], v[206:209], v[4:7]
	v_mfma_f32_16x16x32_bf16 v[0:3], v[156:159], v[206:209], v[0:3]
	s_setprio 0
	s_barrier
	s_add_i32 s89, 0, 0x18000
	s_add_i32 s90, 0, 0x1c000
	v_add_u32_e32 v92, s89, v197
	v_add_u32_e32 v156, s90, v197
	ds_read_b128 v[72:75], v92
	ds_read_b128 v[80:83], v92 offset:1024
	ds_read_b128 v[84:87], v92 offset:2048
	ds_read_b128 v[92:95], v92 offset:3072
	ds_read_b128 v[144:147], v156
	ds_read_b128 v[148:151], v156 offset:1024
	ds_read_b128 v[152:155], v156 offset:2048
	ds_read_b128 v[156:159], v156 offset:3072
	s_add_u32 s58, s58, 0x40000
	s_addc_u32 s59, s59, 0
	s_mov_b32 m0, s65
	v_lshl_add_u64 v[218:219], s[58:59], 0, v[160:161]
	ds_read_b128 v[172:175], v201 offset:32768
	ds_read_b128 v[176:179], v201 offset:33792
	ds_read_b128 v[180:183], v201 offset:34816
	ds_read_b128 v[184:187], v201 offset:35840
	ds_read_b128 v[188:191], v201 offset:36864
	ds_read_b128 v[192:195], v201 offset:37888
	ds_read_b128 v[202:205], v201 offset:38912
	ds_read_b128 v[206:209], v201 offset:39936
	global_load_lds_dwordx4 v[218:219], off
	v_lshl_add_u64 v[218:219], s[58:59], 0, v[162:163]
	s_mov_b32 m0, s66
	s_nop 0
	global_load_lds_dwordx4 v[218:219], off
	s_waitcnt vmcnt(8)
	s_waitcnt lgkmcnt(0)
	s_barrier
	s_setprio 1
	v_mfma_f32_16x16x32_bf16 v[140:143], v[72:75], v[172:175], v[140:143]
	v_mfma_f32_16x16x32_bf16 v[136:139], v[84:87], v[172:175], v[136:139]
	v_mfma_f32_16x16x32_bf16 v[124:127], v[72:75], v[180:183], v[124:127]
	v_mfma_f32_16x16x32_bf16 v[120:123], v[84:87], v[180:183], v[120:123]
	v_mfma_f32_16x16x32_bf16 v[108:111], v[72:75], v[188:191], v[108:111]
	v_mfma_f32_16x16x32_bf16 v[104:107], v[84:87], v[188:191], v[104:107]
	v_mfma_f32_16x16x32_bf16 v[88:91], v[72:75], v[202:205], v[88:91]
	v_mfma_f32_16x16x32_bf16 v[76:79], v[84:87], v[202:205], v[76:79]
	v_mfma_f32_16x16x32_bf16 v[140:143], v[80:83], v[176:179], v[140:143]
	v_mfma_f32_16x16x32_bf16 v[136:139], v[92:95], v[176:179], v[136:139]
	v_mfma_f32_16x16x32_bf16 v[124:127], v[80:83], v[184:187], v[124:127]
	v_mfma_f32_16x16x32_bf16 v[120:123], v[92:95], v[184:187], v[120:123]
	v_mfma_f32_16x16x32_bf16 v[108:111], v[80:83], v[192:195], v[108:111]
	v_mfma_f32_16x16x32_bf16 v[104:107], v[92:95], v[192:195], v[104:107]
	v_mfma_f32_16x16x32_bf16 v[88:91], v[80:83], v[206:209], v[88:91]
	v_mfma_f32_16x16x32_bf16 v[76:79], v[92:95], v[206:209], v[76:79]
	v_mfma_f32_16x16x32_bf16 v[132:135], v[144:147], v[172:175], v[132:135]
	v_mfma_f32_16x16x32_bf16 v[128:131], v[152:155], v[172:175], v[128:131]
	v_mfma_f32_16x16x32_bf16 v[116:119], v[144:147], v[180:183], v[116:119]
	v_mfma_f32_16x16x32_bf16 v[112:115], v[152:155], v[180:183], v[112:115]
	v_mfma_f32_16x16x32_bf16 v[100:103], v[144:147], v[188:191], v[100:103]
	v_mfma_f32_16x16x32_bf16 v[96:99], v[152:155], v[188:191], v[96:99]
	v_mfma_f32_16x16x32_bf16 v[68:71], v[144:147], v[202:205], v[68:71]
	v_mfma_f32_16x16x32_bf16 v[64:67], v[152:155], v[202:205], v[64:67]
	v_mfma_f32_16x16x32_bf16 v[132:135], v[148:151], v[176:179], v[132:135]
	v_mfma_f32_16x16x32_bf16 v[128:131], v[156:159], v[176:179], v[128:131]
	v_mfma_f32_16x16x32_bf16 v[116:119], v[148:151], v[184:187], v[116:119]
	v_mfma_f32_16x16x32_bf16 v[112:115], v[156:159], v[184:187], v[112:115]
	v_mfma_f32_16x16x32_bf16 v[100:103], v[148:151], v[192:195], v[100:103]
	v_mfma_f32_16x16x32_bf16 v[96:99], v[156:159], v[192:195], v[96:99]
	v_mfma_f32_16x16x32_bf16 v[68:71], v[148:151], v[206:209], v[68:71]
	v_mfma_f32_16x16x32_bf16 v[64:67], v[156:159], v[206:209], v[64:67]
	s_setprio 0
	s_barrier
; #define PG8_STAGE(bufoff, gbase, voff) do { _Pragma("unroll") for (int _i = 0; _i < 2; ++_i) \
;         __builtin_amdgcn_global_load_lds((const unsigned*)((const char*)(gbase) + (voff)[_i]), (LAS unsigned*)(lds + (bufoff) + ldsw + _i * 8192), 16, 0, 0); } while (0)
; #define PG8_LDA(dst, b, h) do { _Pragma("unroll") for (int m = 0; m < 4; ++m) _Pragma("unroll") for (int k = 0; k < 2; ++k) dst[m][k] = *(const LAS bf16x8*)(lds + PG8_SA(b, h) + aoff + m * 2048 + k * 1024); } while (0)
; #define PG8_MMA(ai, bj, At, Bt) do { __builtin_amdgcn_s_setprio(1); _Pragma("unroll") for (int m = 0; m < 4; ++m) _Pragma("unroll") for (int n = 0; n < 2; ++n) _Pragma("unroll") for (int k = 0; k < 2; ++k) \
;         acc[ai][bj][m][n] = __builtin_amdgcn_mfma_f32_16x16x32_bf16(Bt[n][k], At[m][k], acc[ai][bj][m][n], 0, 0, 0); __builtin_amdgcn_s_setprio(0); } while (0)
; #define PG8_WAIT_V(n) asm volatile("s_waitcnt vmcnt(" #n ")" ::: "memory")
; #define PG8_WAIT_L(n) asm volatile("s_waitcnt lgkmcnt(" #n ")" ::: "memory")
; #define PG8_BAR __builtin_amdgcn_s_barrier()
; #define PG8_SCHED __builtin_amdgcn_sched_barrier(0)
; template <class Epi, class Sched>
; __device__ __forceinline__ void gemm_phase(LAS unsigned char* lds, const Gemm g, const Sched& S, const Epi& E, const int wid) {
;     ...
;             PG8_LDA(At, 1, 1); PG8_STAGE(PG8_SB(1, 0), b3, voffB); PG8_STAGE(PG8_SB(1, 1), b3 + hstepB, voffB); PG8_STAGE(PG8_SA(1, 0), a3, voffA);
;             PG8_WAIT_V(8); PG8_WAIT_L(0); PG8_BAR; PG8_MMA(1, 0, At, B0); PG8_MMA(1, 1, At, B1); PG8_BAR; PG8_SCHED;
;         }
;         if (wr == 0) PG8_BAR;
	s_add_i32 s58, s89, s63
	v_lshl_add_u64 v[210:211], v[210:211], 0, s[34:35]
	s_mov_b32 m0, s58
	ds_read_b128 v[172:175], v201 offset:49152
	ds_read_b128 v[176:179], v201 offset:50176
	ds_read_b128 v[180:183], v201 offset:51200
	ds_read_b128 v[184:187], v201 offset:52224
	ds_read_b128 v[188:191], v201 offset:53248
	ds_read_b128 v[192:195], v201 offset:54272
	ds_read_b128 v[202:205], v201 offset:55296
	ds_read_b128 v[206:209], v201 offset:56320
	global_load_lds_dwordx4 v[210:211], off
	s_add_i32 m0, s58, 0x2000
	s_add_u32 s56, s56, 0x40080
	v_lshl_add_u64 v[210:211], v[212:213], 0, s[34:35]
	s_addc_u32 s57, s57, 0
	s_add_i32 s58, s90, s63
	global_load_lds_dwordx4 v[210:211], off
	v_lshl_add_u64 v[210:211], s[56:57], 0, v[160:161]
	s_mov_b32 m0, s58
	s_nop 0
	global_load_lds_dwordx4 v[210:211], off
	v_lshl_add_u64 v[210:211], s[56:57], 0, v[162:163]
	s_add_i32 m0, s58, 0x2000
	s_nop 0
	global_load_lds_dwordx4 v[210:211], off
	v_lshl_add_u64 v[210:211], v[214:215], 0, s[34:35]
	s_mov_b32 m0, s72
	s_nop 0
	global_load_lds_dwordx4 v[210:211], off
	v_lshl_add_u64 v[210:211], v[216:217], 0, s[34:35]
	s_mov_b32 m0, s73
	s_nop 0
	global_load_lds_dwordx4 v[210:211], off
	s_waitcnt vmcnt(8)
	s_waitcnt lgkmcnt(0)
	s_barrier
	s_setprio 1
	v_mfma_f32_16x16x32_bf16 v[60:63], v[72:75], v[172:175], v[60:63]
	v_mfma_f32_16x16x32_bf16 v[56:59], v[84:87], v[172:175], v[56:59]
	v_mfma_f32_16x16x32_bf16 v[44:47], v[72:75], v[180:183], v[44:47]
	v_mfma_f32_16x16x32_bf16 v[40:43], v[84:87], v[180:183], v[40:43]
	v_mfma_f32_16x16x32_bf16 v[28:31], v[72:75], v[188:191], v[28:31]
	v_mfma_f32_16x16x32_bf16 v[24:27], v[84:87], v[188:191], v[24:27]
	v_mfma_f32_16x16x32_bf16 v[12:15], v[72:75], v[202:205], v[12:15]
	v_mfma_f32_16x16x32_bf16 v[8:11], v[84:87], v[202:205], v[8:11]
	v_mfma_f32_16x16x32_bf16 v[60:63], v[80:83], v[176:179], v[60:63]
	v_mfma_f32_16x16x32_bf16 v[56:59], v[92:95], v[176:179], v[56:59]
	v_mfma_f32_16x16x32_bf16 v[44:47], v[80:83], v[184:187], v[44:47]
	v_mfma_f32_16x16x32_bf16 v[40:43], v[92:95], v[184:187], v[40:43]
	v_mfma_f32_16x16x32_bf16 v[28:31], v[80:83], v[192:195], v[28:31]
	v_mfma_f32_16x16x32_bf16 v[24:27], v[92:95], v[192:195], v[24:27]
	v_mfma_f32_16x16x32_bf16 v[12:15], v[80:83], v[206:209], v[12:15]
	v_mfma_f32_16x16x32_bf16 v[8:11], v[92:95], v[206:209], v[8:11]
	v_mfma_f32_16x16x32_bf16 v[52:55], v[144:147], v[172:175], v[52:55]
	v_mfma_f32_16x16x32_bf16 v[48:51], v[152:155], v[172:175], v[48:51]
	v_mfma_f32_16x16x32_bf16 v[36:39], v[144:147], v[180:183], v[36:39]
	v_mfma_f32_16x16x32_bf16 v[32:35], v[152:155], v[180:183], v[32:35]
	v_mfma_f32_16x16x32_bf16 v[20:23], v[144:147], v[188:191], v[20:23]
	v_mfma_f32_16x16x32_bf16 v[16:19], v[152:155], v[188:191], v[16:19]
	v_mfma_f32_16x16x32_bf16 v[4:7], v[144:147], v[202:205], v[4:7]
	v_mfma_f32_16x16x32_bf16 v[0:3], v[152:155], v[202:205], v[0:3]
	v_mfma_f32_16x16x32_bf16 v[52:55], v[148:151], v[176:179], v[52:55]
	v_mfma_f32_16x16x32_bf16 v[48:51], v[156:159], v[176:179], v[48:51]
	v_mfma_f32_16x16x32_bf16 v[36:39], v[148:151], v[184:187], v[36:39]
	v_mfma_f32_16x16x32_bf16 v[32:35], v[156:159], v[184:187], v[32:35]
	v_mfma_f32_16x16x32_bf16 v[20:23], v[148:151], v[192:195], v[20:23]
	v_mfma_f32_16x16x32_bf16 v[16:19], v[156:159], v[192:195], v[16:19]
	v_mfma_f32_16x16x32_bf16 v[4:7], v[148:151], v[206:209], v[4:7]
	v_mfma_f32_16x16x32_bf16 v[0:3], v[156:159], v[206:209], v[0:3]
	s_setprio 0
	s_barrier
	s_add_i32 s88, s88, 2
	s_add_u32 s54, s54, 0x100
	s_addc_u32 s55, s55, 0
	s_add_u32 s86, s86, 0x100
	s_addc_u32 s87, s87, 0
	s_cmp_gt_u32 s88, 13
	s_cbranch_scc0 .LBB0_459
	s_and_b64 vcc, exec, s[38:39]
	s_cbranch_vccz .LBB0_462
	s_barrier

; #define PG8_STAGE(bufoff, gbase, voff) do { _Pragma("unroll") for (int _i = 0; _i < 2; ++_i) \
;         __builtin_amdgcn_global_load_lds((const unsigned*)((const char*)(gbase) + (voff)[_i]), (LAS unsigned*)(lds + (bufoff) + ldsw + _i * 8192), 16, 0, 0); } while (0)
; #define PG8_LDA(dst, b, h) do { _Pragma("unroll") for (int m = 0; m < 4; ++m) _Pragma("unroll") for (int k = 0; k < 2; ++k) dst[m][k] = *(const LAS bf16x8*)(lds + PG8_SA(b, h) + aoff + m * 2048 + k * 1024); } while (0)
; #define PG8_LDB(dst, b, h) do { _Pragma("unroll") for (int n = 0; n < 2; ++n) _Pragma("unroll") for (int k = 0; k < 2; ++k) dst[n][k] = *(const LAS bf16x8*)(lds + PG8_SB(b, h) + boff + n * 2048 + k * 1024); } while (0)
; #define PG8_MMA(ai, bj, At, Bt) do { __builtin_amdgcn_s_setprio(1); _Pragma("unroll") for (int m = 0; m < 4; ++m) _Pragma("unroll") for (int n = 0; n < 2; ++n) _Pragma("unroll") for (int k = 0; k < 2; ++k) \
;         acc[ai][bj][m][n] = __builtin_amdgcn_mfma_f32_16x16x32_bf16(Bt[n][k], At[m][k], acc[ai][bj][m][n], 0, 0, 0); __builtin_amdgcn_s_setprio(0); } while (0)
; #define PG8_WAIT_V(n) asm volatile("s_waitcnt vmcnt(" #n ")" ::: "memory")
; #define PG8_WAIT_L(n) asm volatile("s_waitcnt lgkmcnt(" #n ")" ::: "memory")
; #define PG8_BAR __builtin_amdgcn_s_barrier()
; #define PG8_SCHED __builtin_amdgcn_sched_barrier(0)
; template <class Epi, class Sched>
; __device__ __forceinline__ void gemm_phase(LAS unsigned char* lds, const Gemm g, const Sched& S, const Epi& E, const int wid) {
;     ...
;             const bool last = (t == nt - 2);
;             const char* a1 = cA + (size_t)(t + 1) * kstep;
;             const char* a2 = last ? nA : cA + (size_t)(t + 2) * kstep; const char* b2 = last ? nB : cB + (size_t)(t + 2) * kstep;
;             const char* a3 = a2 + kstep; const char* b3 = b2 + kstep;
;             PG8_LDB(B0, 0, 0); PG8_LDB(B1, 0, 1); PG8_SCHED; PG8_LDA(At, 0, 0); PG8_STAGE(PG8_SA(1, 1), a1 + hstepA, voffA);
;             PG8_WAIT_V(8); PG8_WAIT_L(0); PG8_BAR; PG8_MMA(0, 0, At, B0); PG8_MMA(0, 1, At, B1); PG8_BAR; PG8_SCHED;
;             PG8_LDA(At, 0, 1); PG8_STAGE(PG8_SB(0, 0), b2, voffB); PG8_STAGE(PG8_SB(0, 1), b2 + hstepB, voffB); PG8_STAGE(PG8_SA(0, 0), a2, voffA);
;             PG8_WAIT_V(8); PG8_WAIT_L(0); PG8_BAR; PG8_MMA(1, 0, At, B0); PG8_MMA(1, 1, At, B1); PG8_BAR; PG8_SCHED;
.LBB0_546:
	ds_read_b128 v[128:131], v167
	ds_read_b128 v[132:135], v167 offset:1024
	ds_read_b128 v[136:139], v167 offset:2048
	ds_read_b128 v[140:143], v167 offset:3072
	ds_read_b128 v[172:175], v168
	ds_read_b128 v[176:179], v168 offset:1024
	ds_read_b128 v[180:183], v168 offset:2048
	ds_read_b128 v[184:187], v168 offset:3072
	s_add_u32 s48, s46, 0xfffc0080
	s_addc_u32 s49, s47, -1
	s_cmp_eq_u32 s81, 12
	s_cselect_b32 s51, s39, s49
	s_cselect_b32 s50, s77, s48
	s_cselect_b32 s49, s37, s80
	s_cselect_b32 s48, s78, s79
	v_lshl_add_u64 v[164:165], s[46:47], 0, v[156:157]
	s_add_i32 m0, s57, 0xc000
	ds_read_b128 v[188:191], v169
	ds_read_b128 v[192:195], v169 offset:1024
	ds_read_b128 v[196:199], v169 offset:2048
	ds_read_b128 v[200:203], v169 offset:3072
	ds_read_b128 v[204:207], v169 offset:4096
	ds_read_b128 v[208:211], v169 offset:5120
	ds_read_b128 v[212:215], v169 offset:6144
	ds_read_b128 v[216:219], v169 offset:7168
	global_load_lds_dwordx4 v[164:165], off
	v_lshl_add_u64 v[164:165], s[46:47], 0, v[158:159]
	s_add_i32 m0, s57, 0xe000
	s_nop 0
	global_load_lds_dwordx4 v[164:165], off
	s_waitcnt vmcnt(8)
	s_waitcnt lgkmcnt(0)
	s_barrier
	s_setprio 1
	v_mfma_f32_16x16x32_bf16 v[124:127], v[128:131], v[188:191], v[124:127]
	v_mfma_f32_16x16x32_bf16 v[120:123], v[136:139], v[188:191], v[120:123]
	v_mfma_f32_16x16x32_bf16 v[116:119], v[128:131], v[196:199], v[116:119]
	v_mfma_f32_16x16x32_bf16 v[112:115], v[136:139], v[196:199], v[112:115]
	v_mfma_f32_16x16x32_bf16 v[108:111], v[128:131], v[204:207], v[108:111]
	v_mfma_f32_16x16x32_bf16 v[96:99], v[136:139], v[204:207], v[96:99]
	v_mfma_f32_16x16x32_bf16 v[80:83], v[128:131], v[212:215], v[80:83]
	v_mfma_f32_16x16x32_bf16 v[72:75], v[136:139], v[212:215], v[72:75]
	v_mfma_f32_16x16x32_bf16 v[124:127], v[132:135], v[192:195], v[124:127]
	v_mfma_f32_16x16x32_bf16 v[120:123], v[140:143], v[192:195], v[120:123]
	v_mfma_f32_16x16x32_bf16 v[116:119], v[132:135], v[200:203], v[116:119]
	v_mfma_f32_16x16x32_bf16 v[112:115], v[140:143], v[200:203], v[112:115]
	v_mfma_f32_16x16x32_bf16 v[108:111], v[132:135], v[208:211], v[108:111]
	v_mfma_f32_16x16x32_bf16 v[96:99], v[140:143], v[208:211], v[96:99]
	v_mfma_f32_16x16x32_bf16 v[80:83], v[132:135], v[216:219], v[80:83]
	v_mfma_f32_16x16x32_bf16 v[72:75], v[140:143], v[216:219], v[72:75]
	v_mfma_f32_16x16x32_bf16 v[104:107], v[172:175], v[188:191], v[104:107]
	v_mfma_f32_16x16x32_bf16 v[100:103], v[180:183], v[188:191], v[100:103]
	v_mfma_f32_16x16x32_bf16 v[92:95], v[172:175], v[196:199], v[92:95]
	v_mfma_f32_16x16x32_bf16 v[88:91], v[180:183], v[196:199], v[88:91]
	v_mfma_f32_16x16x32_bf16 v[84:87], v[172:175], v[204:207], v[84:87]
	v_mfma_f32_16x16x32_bf16 v[76:79], v[180:183], v[204:207], v[76:79]
	v_mfma_f32_16x16x32_bf16 v[68:71], v[172:175], v[212:215], v[68:71]
	v_mfma_f32_16x16x32_bf16 v[64:67], v[180:183], v[212:215], v[64:67]
	v_mfma_f32_16x16x32_bf16 v[104:107], v[176:179], v[192:195], v[104:107]
	v_mfma_f32_16x16x32_bf16 v[100:103], v[184:187], v[192:195], v[100:103]
	v_mfma_f32_16x16x32_bf16 v[92:95], v[176:179], v[200:203], v[92:95]
	v_mfma_f32_16x16x32_bf16 v[88:91], v[184:187], v[200:203], v[88:91]
	v_mfma_f32_16x16x32_bf16 v[84:87], v[176:179], v[208:211], v[84:87]
	v_mfma_f32_16x16x32_bf16 v[76:79], v[184:187], v[208:211], v[76:79]
	v_mfma_f32_16x16x32_bf16 v[68:71], v[176:179], v[216:219], v[68:71]
	v_mfma_f32_16x16x32_bf16 v[64:67], v[184:187], v[216:219], v[64:67]
	s_setprio 0
	s_barrier
	s_add_i32 s82, s70, s54
	v_lshl_add_u64 v[164:165], s[48:49], 0, v[148:149]
	s_mov_b32 m0, s82
	ds_read_b128 v[188:191], v169 offset:16384
	ds_read_b128 v[192:195], v169 offset:17408
	ds_read_b128 v[196:199], v169 offset:18432
	ds_read_b128 v[200:203], v169 offset:19456
	ds_read_b128 v[204:207], v169 offset:20480
	ds_read_b128 v[208:211], v169 offset:21504
	ds_read_b128 v[212:215], v169 offset:22528
	ds_read_b128 v[216:219], v169 offset:23552
	global_load_lds_dwordx4 v[164:165], off
	s_add_i32 m0, s82, 0x2000
	s_add_u32 s82, s48, 0x40000
	v_lshl_add_u64 v[220:221], s[48:49], 0, v[144:145]
	s_addc_u32 s83, s49, 0
	s_add_i32 s84, s71, s54
	global_load_lds_dwordx4 v[220:221], off
	v_lshl_add_u64 v[222:223], s[82:83], 0, v[148:149]
	s_mov_b32 m0, s84
	v_lshl_add_u64 v[224:225], s[50:51], 0, v[146:147]
	global_load_lds_dwordx4 v[222:223], off
	v_lshl_add_u64 v[222:223], s[82:83], 0, v[144:145]
	s_add_i32 m0, s84, 0x2000
	s_nop 0
	global_load_lds_dwordx4 v[222:223], off
	v_lshl_add_u64 v[222:223], s[50:51], 0, v[150:151]
	s_mov_b32 m0, s57
	s_nop 0
	global_load_lds_dwordx4 v[222:223], off
	s_mov_b32 m0, s58
	s_nop 0
	global_load_lds_dwordx4 v[224:225], off
	s_waitcnt vmcnt(8)
	s_waitcnt lgkmcnt(0)
	s_barrier
; #define PG8_STAGE(bufoff, gbase, voff) do { _Pragma("unroll") for (int _i = 0; _i < 2; ++_i) \
;         __builtin_amdgcn_global_load_lds((const unsigned*)((const char*)(gbase) + (voff)[_i]), (LAS unsigned*)(lds + (bufoff) + ldsw + _i * 8192), 16, 0, 0); } while (0)
; #define PG8_LDA(dst, b, h) do { _Pragma("unroll") for (int m = 0; m < 4; ++m) _Pragma("unroll") for (int k = 0; k < 2; ++k) dst[m][k] = *(const LAS bf16x8*)(lds + PG8_SA(b, h) + aoff + m * 2048 + k * 1024); } while (0)
; #define PG8_LDB(dst, b, h) do { _Pragma("unroll") for (int n = 0; n < 2; ++n) _Pragma("unroll") for (int k = 0; k < 2; ++k) dst[n][k] = *(const LAS bf16x8*)(lds + PG8_SB(b, h) + boff + n * 2048 + k * 1024); } while (0)
; #define PG8_MMA(ai, bj, At, Bt) do { __builtin_amdgcn_s_setprio(1); _Pragma("unroll") for (int m = 0; m < 4; ++m) _Pragma("unroll") for (int n = 0; n < 2; ++n) _Pragma("unroll") for (int k = 0; k < 2; ++k) \
;         acc[ai][bj][m][n] = __builtin_amdgcn_mfma_f32_16x16x32_bf16(Bt[n][k], At[m][k], acc[ai][bj][m][n], 0, 0, 0); __builtin_amdgcn_s_setprio(0); } while (0)
; #define PG8_WAIT_V(n) asm volatile("s_waitcnt vmcnt(" #n ")" ::: "memory")
; #define PG8_WAIT_L(n) asm volatile("s_waitcnt lgkmcnt(" #n ")" ::: "memory")
; #define PG8_BAR __builtin_amdgcn_s_barrier()
; #define PG8_SCHED __builtin_amdgcn_sched_barrier(0)
; template <class Epi, class Sched>
; __device__ __forceinline__ void gemm_phase(LAS unsigned char* lds, const Gemm g, const Sched& S, const Epi& E, const int wid) {
;     ...
;             PG8_WAIT_V(8); PG8_WAIT_L(0); PG8_BAR; PG8_MMA(1, 0, At, B0); PG8_MMA(1, 1, At, B1); PG8_BAR; PG8_SCHED;
;             PG8_LDB(B0, 1, 0); PG8_LDB(B1, 1, 1); PG8_SCHED; PG8_LDA(At, 1, 0); PG8_STAGE(PG8_SA(0, 1), a2 + hstepA, voffA);
;             PG8_WAIT_V(8); PG8_WAIT_L(0); PG8_BAR; PG8_MMA(0, 0, At, B0); PG8_MMA(0, 1, At, B1); PG8_BAR; PG8_SCHED;
	s_setprio 1
	v_mfma_f32_16x16x32_bf16 v[60:63], v[128:131], v[188:191], v[60:63]
	v_mfma_f32_16x16x32_bf16 v[56:59], v[136:139], v[188:191], v[56:59]
	v_mfma_f32_16x16x32_bf16 v[48:51], v[128:131], v[196:199], v[48:51]
	v_mfma_f32_16x16x32_bf16 v[40:43], v[136:139], v[196:199], v[40:43]
	v_mfma_f32_16x16x32_bf16 v[32:35], v[128:131], v[204:207], v[32:35]
	v_mfma_f32_16x16x32_bf16 v[24:27], v[136:139], v[204:207], v[24:27]
	v_mfma_f32_16x16x32_bf16 v[16:19], v[128:131], v[212:215], v[16:19]
	v_mfma_f32_16x16x32_bf16 v[8:11], v[136:139], v[212:215], v[8:11]
	v_mfma_f32_16x16x32_bf16 v[60:63], v[132:135], v[192:195], v[60:63]
	v_mfma_f32_16x16x32_bf16 v[56:59], v[140:143], v[192:195], v[56:59]
	v_mfma_f32_16x16x32_bf16 v[48:51], v[132:135], v[200:203], v[48:51]
	v_mfma_f32_16x16x32_bf16 v[40:43], v[140:143], v[200:203], v[40:43]
	v_mfma_f32_16x16x32_bf16 v[32:35], v[132:135], v[208:211], v[32:35]
	v_mfma_f32_16x16x32_bf16 v[24:27], v[140:143], v[208:211], v[24:27]
	v_mfma_f32_16x16x32_bf16 v[16:19], v[132:135], v[216:219], v[16:19]
	v_mfma_f32_16x16x32_bf16 v[8:11], v[140:143], v[216:219], v[8:11]
	v_mfma_f32_16x16x32_bf16 v[52:55], v[172:175], v[188:191], v[52:55]
	v_mfma_f32_16x16x32_bf16 v[44:47], v[180:183], v[188:191], v[44:47]
	v_mfma_f32_16x16x32_bf16 v[36:39], v[172:175], v[196:199], v[36:39]
	v_mfma_f32_16x16x32_bf16 v[28:31], v[180:183], v[196:199], v[28:31]
	v_mfma_f32_16x16x32_bf16 v[20:23], v[172:175], v[204:207], v[20:23]
	v_mfma_f32_16x16x32_bf16 v[12:15], v[180:183], v[204:207], v[12:15]
	v_mfma_f32_16x16x32_bf16 v[4:7], v[172:175], v[212:215], v[4:7]
	v_mfma_f32_16x16x32_bf16 v[0:3], v[180:183], v[212:215], v[0:3]
	v_mfma_f32_16x16x32_bf16 v[52:55], v[176:179], v[192:195], v[52:55]
	v_mfma_f32_16x16x32_bf16 v[44:47], v[184:187], v[192:195], v[44:47]
	v_mfma_f32_16x16x32_bf16 v[36:39], v[176:179], v[200:203], v[36:39]
	v_mfma_f32_16x16x32_bf16 v[28:31], v[184:187], v[200:203], v[28:31]
	v_mfma_f32_16x16x32_bf16 v[20:23], v[176:179], v[208:211], v[20:23]
	v_mfma_f32_16x16x32_bf16 v[12:15], v[184:187], v[208:211], v[12:15]
	v_mfma_f32_16x16x32_bf16 v[4:7], v[176:179], v[216:219], v[4:7]
	v_mfma_f32_16x16x32_bf16 v[0:3], v[184:187], v[216:219], v[0:3]
	s_setprio 0
	s_barrier
	s_add_i32 s82, 0, 0x18000
	s_add_i32 s83, 0, 0x1c000
	v_add_u32_e32 v140, s82, v166
	v_add_u32_e32 v152, s83, v166
	ds_read_b128 v[128:131], v140
	ds_read_b128 v[132:135], v140 offset:1024
	ds_read_b128 v[136:139], v140 offset:2048
	ds_read_b128 v[140:143], v140 offset:3072
	ds_read_b128 v[172:175], v152
	ds_read_b128 v[176:179], v152 offset:1024
	ds_read_b128 v[180:183], v152 offset:2048
	ds_read_b128 v[184:187], v152 offset:3072
	s_add_u32 s50, s50, 0x40000
	s_addc_u32 s51, s51, 0
	s_mov_b32 m0, s59
	v_lshl_add_u64 v[226:227], s[50:51], 0, v[150:151]
	ds_read_b128 v[188:191], v169 offset:32768
	ds_read_b128 v[192:195], v169 offset:33792
	ds_read_b128 v[196:199], v169 offset:34816
	ds_read_b128 v[200:203], v169 offset:35840
	ds_read_b128 v[204:207], v169 offset:36864
	ds_read_b128 v[208:211], v169 offset:37888
	ds_read_b128 v[212:215], v169 offset:38912
	ds_read_b128 v[216:219], v169 offset:39936
	global_load_lds_dwordx4 v[226:227], off
	v_lshl_add_u64 v[226:227], s[50:51], 0, v[146:147]
	s_mov_b32 m0, s60
	s_nop 0
	global_load_lds_dwordx4 v[226:227], off
	s_waitcnt vmcnt(8)
	s_waitcnt lgkmcnt(0)
	s_barrier
	s_setprio 1
	v_mfma_f32_16x16x32_bf16 v[124:127], v[128:131], v[188:191], v[124:127]
	v_mfma_f32_16x16x32_bf16 v[120:123], v[136:139], v[188:191], v[120:123]
	v_mfma_f32_16x16x32_bf16 v[116:119], v[128:131], v[196:199], v[116:119]
	v_mfma_f32_16x16x32_bf16 v[112:115], v[136:139], v[196:199], v[112:115]
	v_mfma_f32_16x16x32_bf16 v[108:111], v[128:131], v[204:207], v[108:111]
	v_mfma_f32_16x16x32_bf16 v[96:99], v[136:139], v[204:207], v[96:99]
	v_mfma_f32_16x16x32_bf16 v[80:83], v[128:131], v[212:215], v[80:83]
	v_mfma_f32_16x16x32_bf16 v[72:75], v[136:139], v[212:215], v[72:75]
	v_mfma_f32_16x16x32_bf16 v[124:127], v[132:135], v[192:195], v[124:127]
	v_mfma_f32_16x16x32_bf16 v[120:123], v[140:143], v[192:195], v[120:123]
	v_mfma_f32_16x16x32_bf16 v[116:119], v[132:135], v[200:203], v[116:119]
	v_mfma_f32_16x16x32_bf16 v[112:115], v[140:143], v[200:203], v[112:115]
	v_mfma_f32_16x16x32_bf16 v[108:111], v[132:135], v[208:211], v[108:111]
	v_mfma_f32_16x16x32_bf16 v[96:99], v[140:143], v[208:211], v[96:99]
	v_mfma_f32_16x16x32_bf16 v[80:83], v[132:135], v[216:219], v[80:83]
	v_mfma_f32_16x16x32_bf16 v[72:75], v[140:143], v[216:219], v[72:75]
	v_mfma_f32_16x16x32_bf16 v[104:107], v[172:175], v[188:191], v[104:107]
	v_mfma_f32_16x16x32_bf16 v[100:103], v[180:183], v[188:191], v[100:103]
	v_mfma_f32_16x16x32_bf16 v[92:95], v[172:175], v[196:199], v[92:95]
	v_mfma_f32_16x16x32_bf16 v[88:91], v[180:183], v[196:199], v[88:91]
	v_mfma_f32_16x16x32_bf16 v[84:87], v[172:175], v[204:207], v[84:87]
	v_mfma_f32_16x16x32_bf16 v[76:79], v[180:183], v[204:207], v[76:79]
	v_mfma_f32_16x16x32_bf16 v[68:71], v[172:175], v[212:215], v[68:71]
	v_mfma_f32_16x16x32_bf16 v[64:67], v[180:183], v[212:215], v[64:67]
	v_mfma_f32_16x16x32_bf16 v[104:107], v[176:179], v[192:195], v[104:107]
	v_mfma_f32_16x16x32_bf16 v[100:103], v[184:187], v[192:195], v[100:103]
	v_mfma_f32_16x16x32_bf16 v[92:95], v[176:179], v[200:203], v[92:95]
	v_mfma_f32_16x16x32_bf16 v[88:91], v[184:187], v[200:203], v[88:91]
	v_mfma_f32_16x16x32_bf16 v[84:87], v[176:179], v[208:211], v[84:87]
	v_mfma_f32_16x16x32_bf16 v[76:79], v[184:187], v[208:211], v[76:79]
	v_mfma_f32_16x16x32_bf16 v[68:71], v[176:179], v[216:219], v[68:71]
	v_mfma_f32_16x16x32_bf16 v[64:67], v[184:187], v[216:219], v[64:67]
	s_setprio 0
	s_barrier
; #define PG8_STAGE(bufoff, gbase, voff) do { _Pragma("unroll") for (int _i = 0; _i < 2; ++_i) \
;         __builtin_amdgcn_global_load_lds((const unsigned*)((const char*)(gbase) + (voff)[_i]), (LAS unsigned*)(lds + (bufoff) + ldsw + _i * 8192), 16, 0, 0); } while (0)
; #define PG8_LDA(dst, b, h) do { _Pragma("unroll") for (int m = 0; m < 4; ++m) _Pragma("unroll") for (int k = 0; k < 2; ++k) dst[m][k] = *(const LAS bf16x8*)(lds + PG8_SA(b, h) + aoff + m * 2048 + k * 1024); } while (0)
; #define PG8_MMA(ai, bj, At, Bt) do { __builtin_amdgcn_s_setprio(1); _Pragma("unroll") for (int m = 0; m < 4; ++m) _Pragma("unroll") for (int n = 0; n < 2; ++n) _Pragma("unroll") for (int k = 0; k < 2; ++k) \
;         acc[ai][bj][m][n] = __builtin_amdgcn_mfma_f32_16x16x32_bf16(Bt[n][k], At[m][k], acc[ai][bj][m][n], 0, 0, 0); __builtin_amdgcn_s_setprio(0); } while (0)
; #define PG8_WAIT_V(n) asm volatile("s_waitcnt vmcnt(" #n ")" ::: "memory")
; #define PG8_WAIT_L(n) asm volatile("s_waitcnt lgkmcnt(" #n ")" ::: "memory")
; #define PG8_BAR __builtin_amdgcn_s_barrier()
; #define PG8_SCHED __builtin_amdgcn_sched_barrier(0)
; template <class Epi, class Sched>
; __device__ __forceinline__ void gemm_phase(LAS unsigned char* lds, const Gemm g, const Sched& S, const Epi& E, const int wid) {
;     ...
;             PG8_LDA(At, 1, 1); PG8_STAGE(PG8_SB(1, 0), b3, voffB); PG8_STAGE(PG8_SB(1, 1), b3 + hstepB, voffB); PG8_STAGE(PG8_SA(1, 0), a3, voffA);
;             PG8_WAIT_V(8); PG8_WAIT_L(0); PG8_BAR; PG8_MMA(1, 0, At, B0); PG8_MMA(1, 1, At, B1); PG8_BAR; PG8_SCHED;
;         }
;         if (wr == 0) PG8_BAR;
	s_add_i32 s50, s82, s54
	v_lshl_add_u64 v[164:165], v[164:165], 0, s[16:17]
	s_mov_b32 m0, s50
	ds_read_b128 v[188:191], v169 offset:49152
	ds_read_b128 v[192:195], v169 offset:50176
	ds_read_b128 v[196:199], v169 offset:51200
	ds_read_b128 v[200:203], v169 offset:52224
	ds_read_b128 v[204:207], v169 offset:53248
	ds_read_b128 v[208:211], v169 offset:54272
	ds_read_b128 v[212:215], v169 offset:55296
	ds_read_b128 v[216:219], v169 offset:56320
	global_load_lds_dwordx4 v[164:165], off
	s_add_i32 m0, s50, 0x2000
	s_add_u32 s48, s48, 0x40080
	v_lshl_add_u64 v[164:165], v[220:221], 0, s[16:17]
	s_addc_u32 s49, s49, 0
	s_add_i32 s50, s83, s54
	global_load_lds_dwordx4 v[164:165], off
	v_lshl_add_u64 v[164:165], s[48:49], 0, v[148:149]
	s_mov_b32 m0, s50
	s_nop 0
	global_load_lds_dwordx4 v[164:165], off
	v_lshl_add_u64 v[164:165], s[48:49], 0, v[144:145]
	s_add_i32 m0, s50, 0x2000
	s_nop 0
	global_load_lds_dwordx4 v[164:165], off
	v_lshl_add_u64 v[164:165], v[222:223], 0, s[16:17]
	s_mov_b32 m0, s66
	s_nop 0
	global_load_lds_dwordx4 v[164:165], off
	v_lshl_add_u64 v[164:165], v[224:225], 0, s[16:17]
	s_mov_b32 m0, s67
	s_nop 0
	global_load_lds_dwordx4 v[164:165], off
	s_waitcnt vmcnt(8)
	s_waitcnt lgkmcnt(0)
	s_barrier
	s_setprio 1
	v_mfma_f32_16x16x32_bf16 v[60:63], v[128:131], v[188:191], v[60:63]
	v_mfma_f32_16x16x32_bf16 v[56:59], v[136:139], v[188:191], v[56:59]
	v_mfma_f32_16x16x32_bf16 v[48:51], v[128:131], v[196:199], v[48:51]
	v_mfma_f32_16x16x32_bf16 v[40:43], v[136:139], v[196:199], v[40:43]
	v_mfma_f32_16x16x32_bf16 v[32:35], v[128:131], v[204:207], v[32:35]
	v_mfma_f32_16x16x32_bf16 v[24:27], v[136:139], v[204:207], v[24:27]
	v_mfma_f32_16x16x32_bf16 v[16:19], v[128:131], v[212:215], v[16:19]
	v_mfma_f32_16x16x32_bf16 v[8:11], v[136:139], v[212:215], v[8:11]
	v_mfma_f32_16x16x32_bf16 v[60:63], v[132:135], v[192:195], v[60:63]
	v_mfma_f32_16x16x32_bf16 v[56:59], v[140:143], v[192:195], v[56:59]
	v_mfma_f32_16x16x32_bf16 v[48:51], v[132:135], v[200:203], v[48:51]
	v_mfma_f32_16x16x32_bf16 v[40:43], v[140:143], v[200:203], v[40:43]
	v_mfma_f32_16x16x32_bf16 v[32:35], v[132:135], v[208:211], v[32:35]
	v_mfma_f32_16x16x32_bf16 v[24:27], v[140:143], v[208:211], v[24:27]
	v_mfma_f32_16x16x32_bf16 v[16:19], v[132:135], v[216:219], v[16:19]
	v_mfma_f32_16x16x32_bf16 v[8:11], v[140:143], v[216:219], v[8:11]
	v_mfma_f32_16x16x32_bf16 v[52:55], v[172:175], v[188:191], v[52:55]
	v_mfma_f32_16x16x32_bf16 v[44:47], v[180:183], v[188:191], v[44:47]
	v_mfma_f32_16x16x32_bf16 v[36:39], v[172:175], v[196:199], v[36:39]
	v_mfma_f32_16x16x32_bf16 v[28:31], v[180:183], v[196:199], v[28:31]
	v_mfma_f32_16x16x32_bf16 v[20:23], v[172:175], v[204:207], v[20:23]
	v_mfma_f32_16x16x32_bf16 v[12:15], v[180:183], v[204:207], v[12:15]
	v_mfma_f32_16x16x32_bf16 v[4:7], v[172:175], v[212:215], v[4:7]
	v_mfma_f32_16x16x32_bf16 v[0:3], v[180:183], v[212:215], v[0:3]
	v_mfma_f32_16x16x32_bf16 v[52:55], v[176:179], v[192:195], v[52:55]
	v_mfma_f32_16x16x32_bf16 v[44:47], v[184:187], v[192:195], v[44:47]
	v_mfma_f32_16x16x32_bf16 v[36:39], v[176:179], v[200:203], v[36:39]
	v_mfma_f32_16x16x32_bf16 v[28:31], v[184:187], v[200:203], v[28:31]
	v_mfma_f32_16x16x32_bf16 v[20:23], v[176:179], v[208:211], v[20:23]
	v_mfma_f32_16x16x32_bf16 v[12:15], v[184:187], v[208:211], v[12:15]
	v_mfma_f32_16x16x32_bf16 v[4:7], v[176:179], v[216:219], v[4:7]
	v_mfma_f32_16x16x32_bf16 v[0:3], v[184:187], v[216:219], v[0:3]
	s_setprio 0
	s_barrier
	s_add_i32 s81, s81, 2
	s_add_u32 s46, s46, 0x100
	s_addc_u32 s47, s47, 0
	s_add_u32 s79, s79, 0x100
	s_addc_u32 s80, s80, 0
	s_cmp_gt_u32 s81, 13
	s_cbranch_scc0 .LBB0_546
	s_and_b64 vcc, exec, s[18:19]
	s_cbranch_vccz .LBB0_549
	s_barrier

; #define PG8_STAGE(bufoff, gbase, voff) do { _Pragma("unroll") for (int _i = 0; _i < 2; ++_i) \
;         __builtin_amdgcn_global_load_lds((const unsigned*)((const char*)(gbase) + (voff)[_i]), (LAS unsigned*)(lds + (bufoff) + ldsw + _i * 8192), 16, 0, 0); } while (0)
; #define PG8_LDA(dst, b, h) do { _Pragma("unroll") for (int m = 0; m < 4; ++m) _Pragma("unroll") for (int k = 0; k < 2; ++k) dst[m][k] = *(const LAS bf16x8*)(lds + PG8_SA(b, h) + aoff + m * 2048 + k * 1024); } while (0)
; #define PG8_LDB(dst, b, h) do { _Pragma("unroll") for (int n = 0; n < 2; ++n) _Pragma("unroll") for (int k = 0; k < 2; ++k) dst[n][k] = *(const LAS bf16x8*)(lds + PG8_SB(b, h) + boff + n * 2048 + k * 1024); } while (0)
; #define PG8_MMA(ai, bj, At, Bt) do { __builtin_amdgcn_s_setprio(1); _Pragma("unroll") for (int m = 0; m < 4; ++m) _Pragma("unroll") for (int n = 0; n < 2; ++n) _Pragma("unroll") for (int k = 0; k < 2; ++k) \
;         acc[ai][bj][m][n] = __builtin_amdgcn_mfma_f32_16x16x32_bf16(Bt[n][k], At[m][k], acc[ai][bj][m][n], 0, 0, 0); __builtin_amdgcn_s_setprio(0); } while (0)
; #define PG8_WAIT_V(n) asm volatile("s_waitcnt vmcnt(" #n ")" ::: "memory")
; #define PG8_WAIT_L(n) asm volatile("s_waitcnt lgkmcnt(" #n ")" ::: "memory")
; #define PG8_BAR __builtin_amdgcn_s_barrier()
; #define PG8_SCHED __builtin_amdgcn_sched_barrier(0)
; template <class Epi, class Sched>
; __device__ __forceinline__ void gemm_phase(LAS unsigned char* lds, const Gemm g, const Sched& S, const Epi& E, const int wid) {
;     ...
;             const bool last = (t == nt - 2);
;             const char* a1 = cA + (size_t)(t + 1) * kstep;
;             const char* a2 = last ? nA : cA + (size_t)(t + 2) * kstep; const char* b2 = last ? nB : cB + (size_t)(t + 2) * kstep;
;             const char* a3 = a2 + kstep; const char* b3 = b2 + kstep;
;             PG8_LDB(B0, 0, 0); PG8_LDB(B1, 0, 1); PG8_SCHED; PG8_LDA(At, 0, 0); PG8_STAGE(PG8_SA(1, 1), a1 + hstepA, voffA);
;             PG8_WAIT_V(8); PG8_WAIT_L(0); PG8_BAR; PG8_MMA(0, 0, At, B0); PG8_MMA(0, 1, At, B1); PG8_BAR; PG8_SCHED;
;             PG8_LDA(At, 0, 1); PG8_STAGE(PG8_SB(0, 0), b2, voffB); PG8_STAGE(PG8_SB(0, 1), b2 + hstepB, voffB); PG8_STAGE(PG8_SA(0, 0), a2, voffA);
;             PG8_WAIT_V(8); PG8_WAIT_L(0); PG8_BAR; PG8_MMA(1, 0, At, B0); PG8_MMA(1, 1, At, B1); PG8_BAR; PG8_SCHED;
.LBB0_680:
	ds_read_b128 v[128:131], v235
	ds_read_b128 v[132:135], v235 offset:1024
	ds_read_b128 v[136:139], v235 offset:2048
	ds_read_b128 v[140:143], v235 offset:3072
	ds_read_b128 v[144:147], v236
	ds_read_b128 v[148:151], v236 offset:1024
	ds_read_b128 v[152:155], v236 offset:2048
	ds_read_b128 v[156:159], v236 offset:3072
	s_add_u32 s34, s30, 0xfffc0080
	s_addc_u32 s35, s31, -1
	s_cmp_eq_u32 s63, 12
	s_cselect_b32 s37, s21, s35
	s_cselect_b32 s36, s59, s34
	s_cselect_b32 s35, s19, s62
	s_cselect_b32 s34, s60, s61
	v_lshl_add_u64 v[192:193], s[30:31], 0, v[214:215]
	s_add_i32 m0, s44, 0xc000
	ds_read_b128 v[160:163], v237
	ds_read_b128 v[164:167], v237 offset:1024
	ds_read_b128 v[168:171], v237 offset:2048
	ds_read_b128 v[172:175], v237 offset:3072
	ds_read_b128 v[176:179], v237 offset:4096
	ds_read_b128 v[180:183], v237 offset:5120
	ds_read_b128 v[184:187], v237 offset:6144
	ds_read_b128 v[188:191], v237 offset:7168
	global_load_lds_dwordx4 v[192:193], off
	v_lshl_add_u64 v[192:193], s[30:31], 0, v[216:217]
	s_add_i32 m0, s44, 0xe000
	s_nop 0
	global_load_lds_dwordx4 v[192:193], off
	s_waitcnt vmcnt(8)
	s_waitcnt lgkmcnt(0)
	s_barrier
	s_setprio 1
	v_mfma_f32_16x16x32_bf16 v[124:127], v[128:131], v[160:163], v[124:127]
	v_mfma_f32_16x16x32_bf16 v[120:123], v[136:139], v[160:163], v[120:123]
	v_mfma_f32_16x16x32_bf16 v[112:115], v[128:131], v[168:171], v[112:115]
	v_mfma_f32_16x16x32_bf16 v[104:107], v[136:139], v[168:171], v[104:107]
	v_mfma_f32_16x16x32_bf16 v[96:99], v[128:131], v[176:179], v[96:99]
	v_mfma_f32_16x16x32_bf16 v[88:91], v[136:139], v[176:179], v[88:91]
	v_mfma_f32_16x16x32_bf16 v[76:79], v[128:131], v[184:187], v[76:79]
	v_mfma_f32_16x16x32_bf16 v[72:75], v[136:139], v[184:187], v[72:75]
	v_mfma_f32_16x16x32_bf16 v[124:127], v[132:135], v[164:167], v[124:127]
	v_mfma_f32_16x16x32_bf16 v[120:123], v[140:143], v[164:167], v[120:123]
	v_mfma_f32_16x16x32_bf16 v[112:115], v[132:135], v[172:175], v[112:115]
	v_mfma_f32_16x16x32_bf16 v[104:107], v[140:143], v[172:175], v[104:107]
	v_mfma_f32_16x16x32_bf16 v[96:99], v[132:135], v[180:183], v[96:99]
	v_mfma_f32_16x16x32_bf16 v[88:91], v[140:143], v[180:183], v[88:91]
	v_mfma_f32_16x16x32_bf16 v[76:79], v[132:135], v[188:191], v[76:79]
	v_mfma_f32_16x16x32_bf16 v[72:75], v[140:143], v[188:191], v[72:75]
	v_mfma_f32_16x16x32_bf16 v[116:119], v[144:147], v[160:163], v[116:119]
	v_mfma_f32_16x16x32_bf16 v[108:111], v[152:155], v[160:163], v[108:111]
	v_mfma_f32_16x16x32_bf16 v[100:103], v[144:147], v[168:171], v[100:103]
	v_mfma_f32_16x16x32_bf16 v[92:95], v[152:155], v[168:171], v[92:95]
	v_mfma_f32_16x16x32_bf16 v[84:87], v[144:147], v[176:179], v[84:87]
	v_mfma_f32_16x16x32_bf16 v[80:83], v[152:155], v[176:179], v[80:83]
	v_mfma_f32_16x16x32_bf16 v[68:71], v[144:147], v[184:187], v[68:71]
	v_mfma_f32_16x16x32_bf16 v[64:67], v[152:155], v[184:187], v[64:67]
	v_mfma_f32_16x16x32_bf16 v[116:119], v[148:151], v[164:167], v[116:119]
	v_mfma_f32_16x16x32_bf16 v[108:111], v[156:159], v[164:167], v[108:111]
	v_mfma_f32_16x16x32_bf16 v[100:103], v[148:151], v[172:175], v[100:103]
	v_mfma_f32_16x16x32_bf16 v[92:95], v[156:159], v[172:175], v[92:95]
	v_mfma_f32_16x16x32_bf16 v[84:87], v[148:151], v[180:183], v[84:87]
	v_mfma_f32_16x16x32_bf16 v[80:83], v[156:159], v[180:183], v[80:83]
	v_mfma_f32_16x16x32_bf16 v[68:71], v[148:151], v[188:191], v[68:71]
	v_mfma_f32_16x16x32_bf16 v[64:67], v[156:159], v[188:191], v[64:67]
	s_setprio 0
	s_barrier
	s_add_i32 s64, s51, s41
	v_lshl_add_u64 v[192:193], s[34:35], 0, v[210:211]
	s_mov_b32 m0, s64
	ds_read_b128 v[160:163], v237 offset:16384
	ds_read_b128 v[164:167], v237 offset:17408
	ds_read_b128 v[168:171], v237 offset:18432
	ds_read_b128 v[172:175], v237 offset:19456
	ds_read_b128 v[176:179], v237 offset:20480
	ds_read_b128 v[180:183], v237 offset:21504
	ds_read_b128 v[184:187], v237 offset:22528
	ds_read_b128 v[188:191], v237 offset:23552
	global_load_lds_dwordx4 v[192:193], off
	s_add_i32 m0, s64, 0x2000
	s_add_u32 s64, s34, 0x40000
	v_lshl_add_u64 v[194:195], s[34:35], 0, v[208:209]
	s_addc_u32 s65, s35, 0
	s_add_i32 s66, s52, s41
	global_load_lds_dwordx4 v[194:195], off
	v_lshl_add_u64 v[196:197], s[64:65], 0, v[210:211]
	s_mov_b32 m0, s66
	v_lshl_add_u64 v[198:199], s[36:37], 0, v[208:209]
	global_load_lds_dwordx4 v[196:197], off
	v_lshl_add_u64 v[196:197], s[64:65], 0, v[208:209]
	s_add_i32 m0, s66, 0x2000
	s_nop 0
	global_load_lds_dwordx4 v[196:197], off
	v_lshl_add_u64 v[196:197], s[36:37], 0, v[210:211]
	s_mov_b32 m0, s44
	s_nop 0
	global_load_lds_dwordx4 v[196:197], off
	s_mov_b32 m0, s45
	s_nop 0
	global_load_lds_dwordx4 v[198:199], off
	s_waitcnt vmcnt(8)
	s_waitcnt lgkmcnt(0)
	s_barrier
; #define PG8_STAGE(bufoff, gbase, voff) do { _Pragma("unroll") for (int _i = 0; _i < 2; ++_i) \
;         __builtin_amdgcn_global_load_lds((const unsigned*)((const char*)(gbase) + (voff)[_i]), (LAS unsigned*)(lds + (bufoff) + ldsw + _i * 8192), 16, 0, 0); } while (0)
; #define PG8_LDA(dst, b, h) do { _Pragma("unroll") for (int m = 0; m < 4; ++m) _Pragma("unroll") for (int k = 0; k < 2; ++k) dst[m][k] = *(const LAS bf16x8*)(lds + PG8_SA(b, h) + aoff + m * 2048 + k * 1024); } while (0)
; #define PG8_LDB(dst, b, h) do { _Pragma("unroll") for (int n = 0; n < 2; ++n) _Pragma("unroll") for (int k = 0; k < 2; ++k) dst[n][k] = *(const LAS bf16x8*)(lds + PG8_SB(b, h) + boff + n * 2048 + k * 1024); } while (0)
; #define PG8_MMA(ai, bj, At, Bt) do { __builtin_amdgcn_s_setprio(1); _Pragma("unroll") for (int m = 0; m < 4; ++m) _Pragma("unroll") for (int n = 0; n < 2; ++n) _Pragma("unroll") for (int k = 0; k < 2; ++k) \
;         acc[ai][bj][m][n] = __builtin_amdgcn_mfma_f32_16x16x32_bf16(Bt[n][k], At[m][k], acc[ai][bj][m][n], 0, 0, 0); __builtin_amdgcn_s_setprio(0); } while (0)
; #define PG8_WAIT_V(n) asm volatile("s_waitcnt vmcnt(" #n ")" ::: "memory")
; #define PG8_WAIT_L(n) asm volatile("s_waitcnt lgkmcnt(" #n ")" ::: "memory")
; #define PG8_BAR __builtin_amdgcn_s_barrier()
; #define PG8_SCHED __builtin_amdgcn_sched_barrier(0)
; template <class Epi, class Sched>
; __device__ __forceinline__ void gemm_phase(LAS unsigned char* lds, const Gemm g, const Sched& S, const Epi& E, const int wid) {
;     ...
;             PG8_WAIT_V(8); PG8_WAIT_L(0); PG8_BAR; PG8_MMA(1, 0, At, B0); PG8_MMA(1, 1, At, B1); PG8_BAR; PG8_SCHED;
;             PG8_LDB(B0, 1, 0); PG8_LDB(B1, 1, 1); PG8_SCHED; PG8_LDA(At, 1, 0); PG8_STAGE(PG8_SA(0, 1), a2 + hstepA, voffA);
;             PG8_WAIT_V(8); PG8_WAIT_L(0); PG8_BAR; PG8_MMA(0, 0, At, B0); PG8_MMA(0, 1, At, B1); PG8_BAR; PG8_SCHED;
	s_setprio 1
	v_mfma_f32_16x16x32_bf16 v[60:63], v[128:131], v[160:163], v[60:63]
	v_mfma_f32_16x16x32_bf16 v[56:59], v[136:139], v[160:163], v[56:59]
	v_mfma_f32_16x16x32_bf16 v[48:51], v[128:131], v[168:171], v[48:51]
	v_mfma_f32_16x16x32_bf16 v[40:43], v[136:139], v[168:171], v[40:43]
	v_mfma_f32_16x16x32_bf16 v[32:35], v[128:131], v[176:179], v[32:35]
	v_mfma_f32_16x16x32_bf16 v[24:27], v[136:139], v[176:179], v[24:27]
	v_mfma_f32_16x16x32_bf16 v[12:15], v[128:131], v[184:187], v[12:15]
	v_mfma_f32_16x16x32_bf16 v[8:11], v[136:139], v[184:187], v[8:11]
	v_mfma_f32_16x16x32_bf16 v[60:63], v[132:135], v[164:167], v[60:63]
	v_mfma_f32_16x16x32_bf16 v[56:59], v[140:143], v[164:167], v[56:59]
	v_mfma_f32_16x16x32_bf16 v[48:51], v[132:135], v[172:175], v[48:51]
	v_mfma_f32_16x16x32_bf16 v[40:43], v[140:143], v[172:175], v[40:43]
	v_mfma_f32_16x16x32_bf16 v[32:35], v[132:135], v[180:183], v[32:35]
	v_mfma_f32_16x16x32_bf16 v[24:27], v[140:143], v[180:183], v[24:27]
	v_mfma_f32_16x16x32_bf16 v[12:15], v[132:135], v[188:191], v[12:15]
	v_mfma_f32_16x16x32_bf16 v[8:11], v[140:143], v[188:191], v[8:11]
	v_mfma_f32_16x16x32_bf16 v[52:55], v[144:147], v[160:163], v[52:55]
	v_mfma_f32_16x16x32_bf16 v[44:47], v[152:155], v[160:163], v[44:47]
	v_mfma_f32_16x16x32_bf16 v[36:39], v[144:147], v[168:171], v[36:39]
	v_mfma_f32_16x16x32_bf16 v[28:31], v[152:155], v[168:171], v[28:31]
	v_mfma_f32_16x16x32_bf16 v[20:23], v[144:147], v[176:179], v[20:23]
	v_mfma_f32_16x16x32_bf16 v[16:19], v[152:155], v[176:179], v[16:19]
	v_mfma_f32_16x16x32_bf16 v[4:7], v[144:147], v[184:187], v[4:7]
	v_mfma_f32_16x16x32_bf16 v[0:3], v[152:155], v[184:187], v[0:3]
	v_mfma_f32_16x16x32_bf16 v[52:55], v[148:151], v[164:167], v[52:55]
	v_mfma_f32_16x16x32_bf16 v[44:47], v[156:159], v[164:167], v[44:47]
	v_mfma_f32_16x16x32_bf16 v[36:39], v[148:151], v[172:175], v[36:39]
	v_mfma_f32_16x16x32_bf16 v[28:31], v[156:159], v[172:175], v[28:31]
	v_mfma_f32_16x16x32_bf16 v[20:23], v[148:151], v[180:183], v[20:23]
	v_mfma_f32_16x16x32_bf16 v[16:19], v[156:159], v[180:183], v[16:19]
	v_mfma_f32_16x16x32_bf16 v[4:7], v[148:151], v[188:191], v[4:7]
	v_mfma_f32_16x16x32_bf16 v[0:3], v[156:159], v[188:191], v[0:3]
	s_setprio 0
	s_barrier
	s_add_i32 s64, 0, 0x18000
	s_add_i32 s65, 0, 0x1c000
	v_add_u32_e32 v140, s64, v233
	v_add_u32_e32 v156, s65, v233
	ds_read_b128 v[128:131], v140
	ds_read_b128 v[132:135], v140 offset:1024
	ds_read_b128 v[136:139], v140 offset:2048
	ds_read_b128 v[140:143], v140 offset:3072
	ds_read_b128 v[144:147], v156
	ds_read_b128 v[148:151], v156 offset:1024
	ds_read_b128 v[152:155], v156 offset:2048
	ds_read_b128 v[156:159], v156 offset:3072
	s_add_u32 s36, s36, 0x40000
	s_addc_u32 s37, s37, 0
	s_mov_b32 m0, s46
	v_lshl_add_u64 v[200:201], s[36:37], 0, v[210:211]
	ds_read_b128 v[160:163], v237 offset:32768
	ds_read_b128 v[164:167], v237 offset:33792
	ds_read_b128 v[168:171], v237 offset:34816
	ds_read_b128 v[172:175], v237 offset:35840
	ds_read_b128 v[176:179], v237 offset:36864
	ds_read_b128 v[180:183], v237 offset:37888
	ds_read_b128 v[184:187], v237 offset:38912
	ds_read_b128 v[188:191], v237 offset:39936
	global_load_lds_dwordx4 v[200:201], off
	v_lshl_add_u64 v[200:201], s[36:37], 0, v[208:209]
	s_mov_b32 m0, s47
	s_nop 0
	global_load_lds_dwordx4 v[200:201], off
	s_waitcnt vmcnt(8)
	s_waitcnt lgkmcnt(0)
	s_barrier
	s_setprio 1
	v_mfma_f32_16x16x32_bf16 v[124:127], v[128:131], v[160:163], v[124:127]
	v_mfma_f32_16x16x32_bf16 v[120:123], v[136:139], v[160:163], v[120:123]
	v_mfma_f32_16x16x32_bf16 v[112:115], v[128:131], v[168:171], v[112:115]
	v_mfma_f32_16x16x32_bf16 v[104:107], v[136:139], v[168:171], v[104:107]
	v_mfma_f32_16x16x32_bf16 v[96:99], v[128:131], v[176:179], v[96:99]
	v_mfma_f32_16x16x32_bf16 v[88:91], v[136:139], v[176:179], v[88:91]
	v_mfma_f32_16x16x32_bf16 v[76:79], v[128:131], v[184:187], v[76:79]
	v_mfma_f32_16x16x32_bf16 v[72:75], v[136:139], v[184:187], v[72:75]
	v_mfma_f32_16x16x32_bf16 v[124:127], v[132:135], v[164:167], v[124:127]
	v_mfma_f32_16x16x32_bf16 v[120:123], v[140:143], v[164:167], v[120:123]
	v_mfma_f32_16x16x32_bf16 v[112:115], v[132:135], v[172:175], v[112:115]
	v_mfma_f32_16x16x32_bf16 v[104:107], v[140:143], v[172:175], v[104:107]
	v_mfma_f32_16x16x32_bf16 v[96:99], v[132:135], v[180:183], v[96:99]
	v_mfma_f32_16x16x32_bf16 v[88:91], v[140:143], v[180:183], v[88:91]
	v_mfma_f32_16x16x32_bf16 v[76:79], v[132:135], v[188:191], v[76:79]
	v_mfma_f32_16x16x32_bf16 v[72:75], v[140:143], v[188:191], v[72:75]
	v_mfma_f32_16x16x32_bf16 v[116:119], v[144:147], v[160:163], v[116:119]
	v_mfma_f32_16x16x32_bf16 v[108:111], v[152:155], v[160:163], v[108:111]
	v_mfma_f32_16x16x32_bf16 v[100:103], v[144:147], v[168:171], v[100:103]
	v_mfma_f32_16x16x32_bf16 v[92:95], v[152:155], v[168:171], v[92:95]
	v_mfma_f32_16x16x32_bf16 v[84:87], v[144:147], v[176:179], v[84:87]
	v_mfma_f32_16x16x32_bf16 v[80:83], v[152:155], v[176:179], v[80:83]
	v_mfma_f32_16x16x32_bf16 v[68:71], v[144:147], v[184:187], v[68:71]
	v_mfma_f32_16x16x32_bf16 v[64:67], v[152:155], v[184:187], v[64:67]
	v_mfma_f32_16x16x32_bf16 v[116:119], v[148:151], v[164:167], v[116:119]
	v_mfma_f32_16x16x32_bf16 v[108:111], v[156:159], v[164:167], v[108:111]
	v_mfma_f32_16x16x32_bf16 v[100:103], v[148:151], v[172:175], v[100:103]
	v_mfma_f32_16x16x32_bf16 v[92:95], v[156:159], v[172:175], v[92:95]
	v_mfma_f32_16x16x32_bf16 v[84:87], v[148:151], v[180:183], v[84:87]
	v_mfma_f32_16x16x32_bf16 v[80:83], v[156:159], v[180:183], v[80:83]
	v_mfma_f32_16x16x32_bf16 v[68:71], v[148:151], v[188:191], v[68:71]
	v_mfma_f32_16x16x32_bf16 v[64:67], v[156:159], v[188:191], v[64:67]
	s_setprio 0
	s_barrier
; #define PG8_STAGE(bufoff, gbase, voff) do { _Pragma("unroll") for (int _i = 0; _i < 2; ++_i) \
;         __builtin_amdgcn_global_load_lds((const unsigned*)((const char*)(gbase) + (voff)[_i]), (LAS unsigned*)(lds + (bufoff) + ldsw + _i * 8192), 16, 0, 0); } while (0)
; #define PG8_LDA(dst, b, h) do { _Pragma("unroll") for (int m = 0; m < 4; ++m) _Pragma("unroll") for (int k = 0; k < 2; ++k) dst[m][k] = *(const LAS bf16x8*)(lds + PG8_SA(b, h) + aoff + m * 2048 + k * 1024); } while (0)
; #define PG8_MMA(ai, bj, At, Bt) do { __builtin_amdgcn_s_setprio(1); _Pragma("unroll") for (int m = 0; m < 4; ++m) _Pragma("unroll") for (int n = 0; n < 2; ++n) _Pragma("unroll") for (int k = 0; k < 2; ++k) \
;         acc[ai][bj][m][n] = __builtin_amdgcn_mfma_f32_16x16x32_bf16(Bt[n][k], At[m][k], acc[ai][bj][m][n], 0, 0, 0); __builtin_amdgcn_s_setprio(0); } while (0)
; #define PG8_WAIT_V(n) asm volatile("s_waitcnt vmcnt(" #n ")" ::: "memory")
; #define PG8_WAIT_L(n) asm volatile("s_waitcnt lgkmcnt(" #n ")" ::: "memory")
; #define PG8_BAR __builtin_amdgcn_s_barrier()
; #define PG8_SCHED __builtin_amdgcn_sched_barrier(0)
; template <class Epi, class Sched>
; __device__ __forceinline__ void gemm_phase(LAS unsigned char* lds, const Gemm g, const Sched& S, const Epi& E, const int wid) {
;     ...
;             PG8_LDA(At, 1, 1); PG8_STAGE(PG8_SB(1, 0), b3, voffB); PG8_STAGE(PG8_SB(1, 1), b3 + hstepB, voffB); PG8_STAGE(PG8_SA(1, 0), a3, voffA);
;             PG8_WAIT_V(8); PG8_WAIT_L(0); PG8_BAR; PG8_MMA(1, 0, At, B0); PG8_MMA(1, 1, At, B1); PG8_BAR; PG8_SCHED;
;         }
;         if (wr == 0) PG8_BAR;
	s_add_i32 s36, s64, s41
	v_lshl_add_u64 v[192:193], v[192:193], 0, s[12:13]
	s_mov_b32 m0, s36
	ds_read_b128 v[160:163], v237 offset:49152
	ds_read_b128 v[164:167], v237 offset:50176
	ds_read_b128 v[168:171], v237 offset:51200
	ds_read_b128 v[172:175], v237 offset:52224
	ds_read_b128 v[176:179], v237 offset:53248
	ds_read_b128 v[180:183], v237 offset:54272
	ds_read_b128 v[184:187], v237 offset:55296
	ds_read_b128 v[188:191], v237 offset:56320
	global_load_lds_dwordx4 v[192:193], off
	s_add_i32 m0, s36, 0x2000
	s_add_u32 s34, s34, 0x40080
	v_lshl_add_u64 v[192:193], v[194:195], 0, s[12:13]
	s_addc_u32 s35, s35, 0
	s_add_i32 s36, s65, s41
	global_load_lds_dwordx4 v[192:193], off
	v_lshl_add_u64 v[192:193], s[34:35], 0, v[210:211]
	s_mov_b32 m0, s36
	s_nop 0
	global_load_lds_dwordx4 v[192:193], off
	v_lshl_add_u64 v[192:193], s[34:35], 0, v[208:209]
	s_add_i32 m0, s36, 0x2000
	s_nop 0
	global_load_lds_dwordx4 v[192:193], off
	v_lshl_add_u64 v[192:193], v[196:197], 0, s[12:13]
	s_mov_b32 m0, s33
	s_nop 0
	global_load_lds_dwordx4 v[192:193], off
	v_lshl_add_u64 v[192:193], v[198:199], 0, s[12:13]
	s_mov_b32 m0, s50
	s_nop 0
	global_load_lds_dwordx4 v[192:193], off
	s_waitcnt vmcnt(8)
	s_waitcnt lgkmcnt(0)
	s_barrier
	s_setprio 1
	v_mfma_f32_16x16x32_bf16 v[60:63], v[128:131], v[160:163], v[60:63]
	v_mfma_f32_16x16x32_bf16 v[56:59], v[136:139], v[160:163], v[56:59]
	v_mfma_f32_16x16x32_bf16 v[48:51], v[128:131], v[168:171], v[48:51]
	v_mfma_f32_16x16x32_bf16 v[40:43], v[136:139], v[168:171], v[40:43]
	v_mfma_f32_16x16x32_bf16 v[32:35], v[128:131], v[176:179], v[32:35]
	v_mfma_f32_16x16x32_bf16 v[24:27], v[136:139], v[176:179], v[24:27]
	v_mfma_f32_16x16x32_bf16 v[12:15], v[128:131], v[184:187], v[12:15]
	v_mfma_f32_16x16x32_bf16 v[8:11], v[136:139], v[184:187], v[8:11]
	v_mfma_f32_16x16x32_bf16 v[60:63], v[132:135], v[164:167], v[60:63]
	v_mfma_f32_16x16x32_bf16 v[56:59], v[140:143], v[164:167], v[56:59]
	v_mfma_f32_16x16x32_bf16 v[48:51], v[132:135], v[172:175], v[48:51]
	v_mfma_f32_16x16x32_bf16 v[40:43], v[140:143], v[172:175], v[40:43]
	v_mfma_f32_16x16x32_bf16 v[32:35], v[132:135], v[180:183], v[32:35]
	v_mfma_f32_16x16x32_bf16 v[24:27], v[140:143], v[180:183], v[24:27]
	v_mfma_f32_16x16x32_bf16 v[12:15], v[132:135], v[188:191], v[12:15]
	v_mfma_f32_16x16x32_bf16 v[8:11], v[140:143], v[188:191], v[8:11]
	v_mfma_f32_16x16x32_bf16 v[52:55], v[144:147], v[160:163], v[52:55]
	v_mfma_f32_16x16x32_bf16 v[44:47], v[152:155], v[160:163], v[44:47]
	v_mfma_f32_16x16x32_bf16 v[36:39], v[144:147], v[168:171], v[36:39]
	v_mfma_f32_16x16x32_bf16 v[28:31], v[152:155], v[168:171], v[28:31]
	v_mfma_f32_16x16x32_bf16 v[20:23], v[144:147], v[176:179], v[20:23]
	v_mfma_f32_16x16x32_bf16 v[16:19], v[152:155], v[176:179], v[16:19]
	v_mfma_f32_16x16x32_bf16 v[4:7], v[144:147], v[184:187], v[4:7]
	v_mfma_f32_16x16x32_bf16 v[0:3], v[152:155], v[184:187], v[0:3]
	v_mfma_f32_16x16x32_bf16 v[52:55], v[148:151], v[164:167], v[52:55]
	v_mfma_f32_16x16x32_bf16 v[44:47], v[156:159], v[164:167], v[44:47]
	v_mfma_f32_16x16x32_bf16 v[36:39], v[148:151], v[172:175], v[36:39]
	v_mfma_f32_16x16x32_bf16 v[28:31], v[156:159], v[172:175], v[28:31]
	v_mfma_f32_16x16x32_bf16 v[20:23], v[148:151], v[180:183], v[20:23]
	v_mfma_f32_16x16x32_bf16 v[16:19], v[156:159], v[180:183], v[16:19]
	v_mfma_f32_16x16x32_bf16 v[4:7], v[148:151], v[188:191], v[4:7]
	v_mfma_f32_16x16x32_bf16 v[0:3], v[156:159], v[188:191], v[0:3]
	s_setprio 0
	s_barrier
	s_add_i32 s63, s63, 2
	s_add_u32 s30, s30, 0x100
	s_addc_u32 s31, s31, 0
	s_add_u32 s61, s61, 0x100
	s_addc_u32 s62, s62, 0
	s_cmp_gt_u32 s63, 13
	s_cbranch_scc0 .LBB0_680
	s_and_b64 vcc, exec, s[14:15]
	s_cbranch_vccz .LBB0_683
	s_barrier
